# scan loop v6: store addresses are per-lane constants plus a scalar base advanced by SALU (no per-tile address VALU), slow-path wait out of line
# speedup vs baseline: 1.0062x; 1.0062x over previous
.LBB0_563:
	s_and_b32 s13, s6, 0xff
	s_lshl_b32 s0, s13, 2
	v_mov_b32_e32 v0, s0
	global_load_dword v2, v0, s[38:39]
	s_lshl_b32 s4, s13, 6
	v_or_b32_e32 v0, s4, v174
	v_lshlrev_b32_e32 v3, 2, v0
	global_load_dword v21, v3, s[58:59]
	global_load_dword v20, v3, s[36:37]
	s_and_b32 s2, s10, 0x1800
	v_or_b32_e32 v1, s2, v182
	v_lshlrev_b32_e32 v1, 3, v1
	s_bfe_u32 s0, s12, 0x70001
	v_and_b32_e32 v1, 0xc180, v1
	v_or_b32_e32 v1, s0, v1
	v_lshlrev_b32_e32 v132, 10, v1
	v_lshl_add_u64 v[150:151], v[144:145], 0, v[132:133]
	v_lshl_add_u64 v[152:153], v[146:147], 0, v[132:133]
	v_lshl_add_u64 v[154:155], v[148:149], 0, v[132:133]
	v_lshlrev_b32_e32 v132, 6, v0
	v_lshl_add_u64 v[0:1], v[136:137], 0, v[132:133]
	global_load_dwordx4 v[4:7], v[0:1], off
	global_load_dwordx4 v[8:11], v[0:1], off offset:16
	v_lshl_add_u64 v[0:1], v[134:135], 0, v[132:133]
	global_load_dwordx4 v[12:15], v[0:1], off
	global_load_dwordx4 v[16:19], v[0:1], off offset:16
	v_or_b32_e32 v0, s4, v173
	v_lshlrev_b32_e32 v22, 2, v0
	v_or_b32_e32 v132, 0x800, v132
	s_bfe_u32 s16, s6, 0x70001
	v_mov_b32_e32 v188, 0
	v_mov_b32_e32 v189, v133
	s_waitcnt vmcnt(6)
	v_mul_f32_e32 v0, 0x3fb8aa3b, v2
	v_exp_f32_e32 v0, v0
	global_load_dword v2, v22, s[58:59]
	global_load_dword v1, v22, s[36:37]
	s_waitcnt vmcnt(7)
	v_mov_b32_e32 v22, v21
	v_mov_b32_e32 v25, v21
	v_mul_f32_e32 v23, v0, v21
	s_waitcnt vmcnt(6)
	v_mul_f32_e32 v24, v0, v20
	v_mul_f32_e32 v23, 0x3fb8aa3b, v23
	v_mul_f32_e32 v24, 0.15915494, v24
	v_exp_f32_e32 v23, v23
	v_sin_f32_e32 v26, v24
	v_cos_f32_e32 v24, v24
	v_mov_b32_e32 v27, v20
	v_mul_f32_e32 v28, v23, v26
	v_fma_f32 v29, v23, v24, -1.0
	v_mov_b32_e32 v24, v28
	v_mov_b32_e32 v26, v29
	v_pk_mul_f32 v[30:31], v[20:21], v[28:29]
	v_pk_mul_f32 v[22:23], v[22:23], v[24:25] op_sel_hi:[0,1]
	v_pk_mul_f32 v[20:21], v[20:21], v[26:27] op_sel_hi:[0,1]
	v_add_f32_e32 v28, v30, v31
	v_add_f32_e32 v21, v23, v21
	v_sub_f32_e32 v22, v22, v20
	v_div_scale_f32 v20, s[0:1], v21, v21, v28
	v_div_scale_f32 v24, s[0:1], v21, v21, v22
	v_rcp_f32_e32 v25, v20
	v_rcp_f32_e32 v26, v24
	v_div_scale_f32 v23, vcc, v28, v21, v28
	v_fma_f32 v29, -v20, v25, 1.0
	v_fma_f32 v30, -v24, v26, 1.0
	v_fmac_f32_e32 v25, v29, v25
	v_div_scale_f32 v27, s[0:1], v22, v21, v22
	v_fmac_f32_e32 v26, v30, v26
	v_mul_f32_e32 v29, v23, v25
	v_mul_f32_e32 v30, v27, v26
	v_fma_f32 v31, -v20, v29, v23
	v_fma_f32 v32, -v24, v30, v27
	v_fmac_f32_e32 v29, v31, v25
	v_fmac_f32_e32 v30, v32, v26
	v_fma_f32 v20, -v20, v29, v23
	v_fma_f32 v23, -v24, v30, v27
	v_div_fmas_f32 v20, v20, v25, v29
	s_mov_b64 vcc, s[0:1]
	v_div_fmas_f32 v23, v23, v26, v30
	v_div_fixup_f32 v22, v23, v21, v22
	v_div_fixup_f32 v20, v20, v21, v28
	s_waitcnt vmcnt(5)
	v_pk_mul_f32 v[24:25], v[4:5], v[22:23] op_sel_hi:[1,0]
	v_pk_mul_f32 v[26:27], v[6:7], v[22:23] op_sel_hi:[1,0]
	s_waitcnt vmcnt(4)
	v_pk_mul_f32 v[28:29], v[8:9], v[22:23] op_sel_hi:[1,0]
	v_pk_mul_f32 v[30:31], v[10:11], v[22:23] op_sel_hi:[1,0]
	s_waitcnt vmcnt(3)
	v_pk_mul_f32 v[32:33], v[12:13], v[22:23] op_sel_hi:[1,0]
	v_pk_mul_f32 v[34:35], v[14:15], v[22:23] op_sel_hi:[1,0]
	s_waitcnt vmcnt(2)
	v_pk_mul_f32 v[36:37], v[16:17], v[22:23] op_sel_hi:[1,0]
	v_pk_mul_f32 v[22:23], v[18:19], v[22:23] op_sel_hi:[1,0]
	v_pk_fma_f32 v[14:15], v[14:15], v[20:21], v[26:27] op_sel_hi:[1,0,1] neg_lo:[0,0,1] neg_hi:[0,0,1]
	v_pk_fma_f32 v[12:13], v[12:13], v[20:21], v[24:25] op_sel_hi:[1,0,1] neg_lo:[0,0,1] neg_hi:[0,0,1]
	v_pk_fma_f32 v[18:19], v[18:19], v[20:21], v[30:31] op_sel_hi:[1,0,1] neg_lo:[0,0,1] neg_hi:[0,0,1]
	v_pk_fma_f32 v[16:17], v[16:17], v[20:21], v[28:29] op_sel_hi:[1,0,1] neg_lo:[0,0,1] neg_hi:[0,0,1]
	v_pk_fma_f32 v[6:7], v[6:7], v[20:21], v[34:35] op_sel_hi:[1,0,1]
	v_pk_fma_f32 v[4:5], v[4:5], v[20:21], v[32:33] op_sel_hi:[1,0,1]
	v_pk_fma_f32 v[10:11], v[10:11], v[20:21], v[22:23] op_sel_hi:[1,0,1]
	v_pk_fma_f32 v[8:9], v[8:9], v[20:21], v[36:37] op_sel_hi:[1,0,1]
	v_cvt_pk_bf16_f32 v104, v12, v13
	v_cvt_pk_bf16_f32 v105, v14, v15
	v_cvt_pk_bf16_f32 v106, v16, v17
	v_cvt_pk_bf16_f32 v107, v18, v19
	v_cvt_pk_bf16_f32 v92, v4, v5
	v_cvt_pk_bf16_f32 v93, v6, v7
	s_nop 0
	v_cvt_pk_bf16_f32 v94, v8, v9
	v_cvt_pk_bf16_f32 v95, v10, v11
	v_lshl_or_b32 v58, s13, 12, v183
	v_mov_b32_e32 v59, 0
	v_lshl_add_u64 v[60:61], v[138:139], 0, v[58:59]
	v_lshl_add_u64 v[62:63], v[140:141], 0, v[58:59]
	global_load_dwordx4 v[196:199], v[60:61], off
	global_load_dwordx4 v[200:203], v[62:63], off
	global_load_dwordx4 v[204:207], v[60:61], off offset:32
	global_load_dwordx4 v[208:211], v[62:63], off offset:32
	global_load_dwordx4 v[212:215], v[60:61], off offset:64
	global_load_dwordx4 v[216:219], v[62:63], off offset:64
	global_load_dwordx4 v[220:223], v[60:61], off offset:96
	global_load_dwordx4 v[224:227], v[62:63], off offset:96
	global_load_dwordx4 v[228:231], v[60:61], off offset:128
	global_load_dwordx4 v[232:235], v[62:63], off offset:128
	global_load_dwordx4 v[236:239], v[60:61], off offset:160
	global_load_dwordx4 v[240:243], v[62:63], off offset:160
	global_load_dwordx4 v[244:247], v[60:61], off offset:192
	global_load_dwordx4 v[40:43], v[62:63], off offset:192
	global_load_dwordx4 v[44:47], v[60:61], off offset:224
	global_load_dwordx4 v[48:51], v[62:63], off offset:224
	global_load_dword v21, v3, s[58:59] offset:128
	global_load_dword v20, v3, s[36:37] offset:128
	v_lshl_add_u64 v[12:13], v[136:137], 0, v[132:133]
	v_lshl_add_u64 v[22:23], v[134:135], 0, v[132:133]
	global_load_dwordx4 v[4:7], v[12:13], off
	global_load_dwordx4 v[8:11], v[12:13], off offset:16
	s_nop 0
	global_load_dwordx4 v[12:15], v[22:23], off
	global_load_dwordx4 v[16:19], v[22:23], off offset:16
	v_lshl_or_b32 v132, s13, 12, v183
	v_lshl_add_u64 v[22:23], v[138:139], 0, v[132:133]
	s_waitcnt vmcnt(7)
	v_mul_f32_e32 v2, v2, v0
	v_mul_f32_e32 v2, 0x3fb8aa3b, v2
	v_exp_f32_e32 v2, v2
	s_waitcnt vmcnt(5)
	v_mul_f32_e32 v3, v0, v21
	s_waitcnt vmcnt(4)
	v_mul_f32_e32 v25, v0, v20
	v_mul_f32_e32 v3, 0x3fb8aa3b, v3
	v_mul_f32_e32 v25, 0.15915494, v25
	v_exp_f32_e32 v3, v3
	v_sin_f32_e32 v26, v25
	v_cos_f32_e32 v25, v25
	v_mov_b32_e32 v24, v21
	v_mov_b32_e32 v27, v21
	v_mul_f32_e32 v30, v3, v26
	v_fma_f32 v31, v3, v25, -1.0
	v_mov_b32_e32 v29, v20
	v_mov_b32_e32 v26, v30
	v_mov_b32_e32 v28, v31
	v_pk_mul_f32 v[32:33], v[20:21], v[30:31]
	v_pk_mul_f32 v[24:25], v[24:25], v[26:27] op_sel_hi:[0,1]
	v_pk_mul_f32 v[20:21], v[20:21], v[28:29] op_sel_hi:[0,1]
	v_add_f32_e32 v3, v32, v33
	v_add_f32_e32 v21, v25, v21
	v_sub_f32_e32 v24, v24, v20
	v_div_scale_f32 v20, s[0:1], v21, v21, v3
	v_div_scale_f32 v26, s[0:1], v21, v21, v24
	v_rcp_f32_e32 v27, v20
	v_rcp_f32_e32 v28, v26
	v_div_scale_f32 v25, vcc, v3, v21, v3
	v_fma_f32 v30, -v20, v27, 1.0
	v_fma_f32 v31, -v26, v28, 1.0
	v_fmac_f32_e32 v27, v30, v27
	v_div_scale_f32 v29, s[0:1], v24, v21, v24
	v_fmac_f32_e32 v28, v31, v28
	v_mul_f32_e32 v30, v25, v27
	v_mul_f32_e32 v31, v29, v28
	v_fma_f32 v32, -v20, v30, v25
	v_fma_f32 v33, -v26, v31, v29
	v_fmac_f32_e32 v30, v32, v27
	v_fmac_f32_e32 v31, v33, v28
	v_fma_f32 v20, -v20, v30, v25
	v_fma_f32 v25, -v26, v31, v29
	v_div_fmas_f32 v20, v20, v27, v30
	s_mov_b64 vcc, s[0:1]
	v_div_fixup_f32 v20, v20, v21, v3
	v_div_fmas_f32 v3, v25, v28, v31
	v_div_fixup_f32 v24, v3, v21, v24
	s_waitcnt vmcnt(3)
	v_pk_mul_f32 v[26:27], v[4:5], v[24:25] op_sel_hi:[1,0]
	v_pk_mul_f32 v[28:29], v[6:7], v[24:25] op_sel_hi:[1,0]
	s_waitcnt vmcnt(2)
	v_pk_mul_f32 v[30:31], v[8:9], v[24:25] op_sel_hi:[1,0]
	v_pk_mul_f32 v[32:33], v[10:11], v[24:25] op_sel_hi:[1,0]
	s_waitcnt vmcnt(1)
	v_pk_mul_f32 v[34:35], v[12:13], v[24:25] op_sel_hi:[1,0]
	v_pk_mul_f32 v[36:37], v[14:15], v[24:25] op_sel_hi:[1,0]
	s_waitcnt vmcnt(0)
	v_pk_mul_f32 v[38:39], v[16:17], v[24:25] op_sel_hi:[1,0]
	v_pk_mul_f32 v[24:25], v[18:19], v[24:25] op_sel_hi:[1,0]
	v_pk_fma_f32 v[12:13], v[12:13], v[20:21], v[26:27] op_sel_hi:[1,0,1] neg_lo:[0,0,1] neg_hi:[0,0,1]
	v_pk_fma_f32 v[6:7], v[6:7], v[20:21], v[36:37] op_sel_hi:[1,0,1]
	v_pk_fma_f32 v[4:5], v[4:5], v[20:21], v[34:35] op_sel_hi:[1,0,1]
	v_pk_fma_f32 v[10:11], v[10:11], v[20:21], v[24:25] op_sel_hi:[1,0,1]
	v_pk_fma_f32 v[8:9], v[8:9], v[20:21], v[38:39] op_sel_hi:[1,0,1]
	v_cvt_pk_bf16_f32 v116, v12, v13
	v_lshl_add_u64 v[12:13], v[140:141], 0, v[132:133]
	v_pk_fma_f32 v[14:15], v[14:15], v[20:21], v[28:29] op_sel_hi:[1,0,1] neg_lo:[0,0,1] neg_hi:[0,0,1]
	v_pk_fma_f32 v[18:19], v[18:19], v[20:21], v[32:33] op_sel_hi:[1,0,1] neg_lo:[0,0,1] neg_hi:[0,0,1]
	v_pk_fma_f32 v[16:17], v[16:17], v[20:21], v[30:31] op_sel_hi:[1,0,1] neg_lo:[0,0,1] neg_hi:[0,0,1]
	v_cvt_pk_bf16_f32 v117, v14, v15
	s_lshl_b32 s1, s6, 3
	v_cvt_pk_bf16_f32 v118, v16, v17
	v_cvt_pk_bf16_f32 v119, v18, v19
	v_cvt_pk_bf16_f32 v112, v4, v5
	v_cvt_pk_bf16_f32 v113, v6, v7
	v_cvt_pk_bf16_f32 v114, v8, v9
	v_cvt_pk_bf16_f32 v115, v10, v11
	s_and_b32 s15, s1, 0x1800
	v_or_b32_e32 v3, s15, v174
	v_lshlrev_b32_e32 v3, 3, v3
	s_lshl_b32 s0, s6, 4
	v_and_b32_e32 v3, 0xc080, v3
	s_and_b32 s14, s0, 16
	v_or_b32_e32 v3, s16, v3
	v_or_b32_e32 v132, s14, v176
	v_lshl_or_b32 v3, v3, 9, v177
	v_or3_b32 v14, s14, v175, v3
	v_or_b32_e32 v3, v3, v132
	v_lshlrev_b32_e32 v3, 1, v3
	v_lshlrev_b32_e32 v14, 1, v14
	v_or_b32_e32 v15, 16, v3
	v_mul_f32_e32 v0, v0, v1
	v_mul_f32_e32 v1, 0.15915494, v0
	v_cos_f32_e32 v0, v1
	v_sin_f32_e32 v1, v1
	s_mov_b64 s[0:1], 0
	s_mov_b32 s16, 0
	v_pk_mul_f32 v[198:199], v[126:127], v[198:199]
	v_pk_mul_f32 v[196:197], v[124:125], v[196:197]
	v_pk_mul_f32 v[202:203], v[130:131], v[202:203]
	v_pk_mul_f32 v[200:201], v[128:129], v[200:201]
	s_nop 0
	v_cvt_pk_bf16_f32 v64, v196, v200
	v_cvt_pk_bf16_f32 v65, v197, v201
	v_cvt_pk_bf16_f32 v66, v198, v202
	v_cvt_pk_bf16_f32 v67, v199, v203
	v_pk_mul_f32 v[206:207], v[126:127], v[206:207]
	v_pk_mul_f32 v[204:205], v[124:125], v[204:205]
	v_pk_mul_f32 v[210:211], v[130:131], v[210:211]
	v_pk_mul_f32 v[208:209], v[128:129], v[208:209]
	s_nop 0
	v_cvt_pk_bf16_f32 v68, v204, v208
	v_cvt_pk_bf16_f32 v69, v205, v209
	v_cvt_pk_bf16_f32 v70, v206, v210
	v_cvt_pk_bf16_f32 v71, v207, v211
	v_pk_mul_f32 v[214:215], v[126:127], v[214:215]
	v_pk_mul_f32 v[212:213], v[124:125], v[212:213]
	v_pk_mul_f32 v[218:219], v[130:131], v[218:219]
	v_pk_mul_f32 v[216:217], v[128:129], v[216:217]
	s_nop 0
	v_cvt_pk_bf16_f32 v72, v212, v216
	v_cvt_pk_bf16_f32 v73, v213, v217
	v_cvt_pk_bf16_f32 v74, v214, v218
	v_cvt_pk_bf16_f32 v75, v215, v219
	v_pk_mul_f32 v[222:223], v[126:127], v[222:223]
	v_pk_mul_f32 v[220:221], v[124:125], v[220:221]
	v_pk_mul_f32 v[226:227], v[130:131], v[226:227]
	v_pk_mul_f32 v[224:225], v[128:129], v[224:225]
	s_nop 0
	v_cvt_pk_bf16_f32 v76, v220, v224
	v_cvt_pk_bf16_f32 v77, v221, v225
	v_cvt_pk_bf16_f32 v78, v222, v226
	v_cvt_pk_bf16_f32 v79, v223, v227
	v_pk_mul_f32 v[230:231], v[126:127], v[230:231]
	v_pk_mul_f32 v[228:229], v[124:125], v[228:229]
	v_pk_mul_f32 v[234:235], v[130:131], v[234:235]
	v_pk_mul_f32 v[232:233], v[128:129], v[232:233]
	s_nop 0
	v_cvt_pk_bf16_f32 v84, v228, v232
	v_cvt_pk_bf16_f32 v85, v229, v233
	v_cvt_pk_bf16_f32 v86, v230, v234
	v_cvt_pk_bf16_f32 v87, v231, v235
	v_pk_mul_f32 v[238:239], v[126:127], v[238:239]
	v_pk_mul_f32 v[236:237], v[124:125], v[236:237]
	v_pk_mul_f32 v[242:243], v[130:131], v[242:243]
	v_pk_mul_f32 v[240:241], v[128:129], v[240:241]
	s_nop 0
	v_cvt_pk_bf16_f32 v88, v236, v240
	v_cvt_pk_bf16_f32 v89, v237, v241
	v_cvt_pk_bf16_f32 v90, v238, v242
	v_cvt_pk_bf16_f32 v91, v239, v243
	v_pk_mul_f32 v[246:247], v[126:127], v[246:247]
	v_pk_mul_f32 v[244:245], v[124:125], v[244:245]
	v_pk_mul_f32 v[42:43], v[130:131], v[42:43]
	v_pk_mul_f32 v[40:41], v[128:129], v[40:41]
	s_nop 0
	v_cvt_pk_bf16_f32 v96, v244, v40
	v_cvt_pk_bf16_f32 v97, v245, v41
	v_cvt_pk_bf16_f32 v98, v246, v42
	v_cvt_pk_bf16_f32 v99, v247, v43
	v_lshl_add_u64 v[12:13], v[142:143], 0, s[4:5]
	s_bfe_u32 s4, s6, 0x10001
	v_pk_mul_f32 v[46:47], v[126:127], v[46:47]
	v_pk_mul_f32 v[44:45], v[124:125], v[44:45]
	v_pk_mul_f32 v[50:51], v[130:131], v[50:51]
	v_pk_mul_f32 v[48:49], v[128:129], v[48:49]
	s_nop 0
	v_cvt_pk_bf16_f32 v108, v44, v48
	v_cvt_pk_bf16_f32 v109, v45, v49
	v_cvt_pk_bf16_f32 v110, v46, v50
	v_cvt_pk_bf16_f32 v111, v47, v51
	global_load_dwordx4 v[100:103], v[12:13], off
	global_load_dwordx4 v[80:83], v[12:13], off offset:32
	global_load_dwordx4 v[120:123], v14, s[54:55]
	global_load_dwordx2 v[158:159], v3, s[54:55]
	global_load_dwordx2 v[156:157], v15, s[54:55]
	v_or_b32_e32 v3, s2, v174
	v_pk_mul_f32 v[160:161], v[0:1], v[2:3] op_sel_hi:[1,0]
	v_lshrrev_b32_e32 v187, 3, v3
	v_pk_mov_b32 v[162:163], v[160:161], v[160:161] op_sel:[1,0]
	v_mov_b32_e32 v164, v160
	v_mov_b32_e32 v165, v160
	v_mov_b32_e32 v166, v161
	v_mov_b32_e32 v167, v161
	v_mov_b32_e32 v184, 0xbdd2d3e8
	global_load_dwordx4 v[168:171], v[152:153], off
	s_add_u32 s0, s0, 0x40000
	s_addc_u32 s1, s1, 0
	v_lshl_add_u64 v[216:217], v[152:153], 0, s[0:1]
	global_load_dwordx4 v[156:159], v[216:217], off
	s_add_u32 s0, s0, 0x40000
	s_addc_u32 s1, s1, 0
	v_lshl_add_u64 v[216:217], v[152:153], 0, s[0:1]
	global_load_dwordx4 v[178:181], v[216:217], off
	s_and_b32 s18, s16, 0x2000
	s_and_b32 s17, s2, 0x1f00
	s_or_b32 s17, s17, s13
	s_lshl_b32 s17, s17, 12
	s_and_b32 s17, s17, 0x1ffc000
	v_add_u32_e32 v222, s2, v174
	v_and_or_b32 v223, v187, 14, s4
	v_lshlrev_b32_e32 v225, 5, v222
	v_lshlrev_b32_e32 v226, 1, v222
	v_lshl_or_b32 v227, v223, 9, s18
	v_and_b32_e32 v222, 0x1e0, v225
	v_and_b32_e32 v223, 16, v226
	v_or_b32_e32 v224, v222, v132
	v_bitop3_b32 v222, v222, v223, v132 bitop3:0x36
	v_or_b32_e32 v225, s17, v227
	v_bitop3_b32 v226, v224, v223, 8 bitop3:0x36
	v_or_b32_e32 v227, v222, v225
	v_or_b32_e32 v254, v226, v225
	v_lshlrev_b32_e32 v253, 1, v227
	v_lshlrev_b32_e32 v254, 1, v254
	s_mov_b64 s[14:15], s[90:91]
	s_branch .Lscan_tile
.Lscan_w3_0:
	s_waitcnt vmcnt(3)
	s_branch .Lscan_go_0

.Lscan_go_0:
	v_mfma_f32_32x32x16_bf16 v[0:15], v[120:123], v[104:107], 0
	s_addk_i32 s16, 0x800
	v_mfma_f32_32x32x16_bf16 v[16:31], v[120:123], v[116:119], 0
	v_mfma_f32_32x32x16_bf16 v[32:47], v[120:123], v[92:95], 0
	v_mfma_f32_32x32x16_bf16 v[196:211], v[120:123], v[112:115], 0
	v_mov_b32_e32 v218, v120
	v_mov_b32_e32 v219, v121
	v_mov_b32_e32 v220, v122
	v_mov_b32_e32 v221, v123
	s_nop 0
	v_permlane32_swap_b32_e32 v218, v220
	v_permlane32_swap_b32_e32 v219, v221
	s_add_u32 s0, s0, 0x40000
	s_addc_u32 s1, s1, 0
	v_lshl_add_u64 v[216:217], v[152:153], 0, s[0:1]
	global_load_dwordx4 v[120:123], v[216:217], off
	v_lshlrev_b32_e32 v228, 16, v218
	v_and_b32_e32 v229, 0xffff0000, v218
	v_lshlrev_b32_e32 v230, 16, v219
	v_and_b32_e32 v231, 0xffff0000, v219
	v_lshlrev_b32_e32 v232, 16, v220
	v_and_b32_e32 v233, 0xffff0000, v220
	v_lshlrev_b32_e32 v251, 16, v221
	v_and_b32_e32 v252, 0xffff0000, v221
	v_permlane32_swap_b32_e32 v0, v16
	v_permlane32_swap_b32_e32 v1, v17
	v_permlane32_swap_b32_e32 v2, v18
	v_permlane32_swap_b32_e32 v3, v19
	v_permlane32_swap_b32_e32 v4, v20
	v_permlane32_swap_b32_e32 v5, v21
	v_permlane32_swap_b32_e32 v6, v22
	v_permlane32_swap_b32_e32 v7, v23
	v_permlane32_swap_b32_e32 v8, v24
	v_permlane32_swap_b32_e32 v9, v25
	v_permlane32_swap_b32_e32 v10, v26
	v_permlane32_swap_b32_e32 v11, v27
	v_permlane32_swap_b32_e32 v12, v28
	v_permlane32_swap_b32_e32 v13, v29
	v_permlane32_swap_b32_e32 v14, v30
	v_permlane32_swap_b32_e32 v15, v31
	v_permlane32_swap_b32_e32 v32, v196
	v_permlane32_swap_b32_e32 v33, v197
	v_permlane32_swap_b32_e32 v34, v198
	v_permlane32_swap_b32_e32 v35, v199
	v_permlane32_swap_b32_e32 v36, v200
	v_permlane32_swap_b32_e32 v37, v201
	v_permlane32_swap_b32_e32 v38, v202
	v_permlane32_swap_b32_e32 v39, v203
	v_permlane32_swap_b32_e32 v40, v204
	v_permlane32_swap_b32_e32 v41, v205
	v_permlane32_swap_b32_e32 v42, v206
	v_permlane32_swap_b32_e32 v43, v207
	v_permlane32_swap_b32_e32 v44, v208
	v_permlane32_swap_b32_e32 v45, v209
	v_permlane32_swap_b32_e32 v46, v210
	v_permlane32_swap_b32_e32 v47, v211
	v_fmac_f32_e32 v0, v160, v188
	v_fmac_f32_e32 v32, v160, v189
	v_fma_f32 v0, -v161, v189, v0
	v_fmac_f32_e32 v32, v161, v188
	v_fmac_f32_e32 v1, v160, v0
	v_fmac_f32_e32 v33, v160, v32
	v_cvt_pk_bf16_f32 v212, v0, v32
	v_fma_f32 v1, -v161, v32, v1
	v_fmac_f32_e32 v33, v161, v0
	ds_write_b32 v185, v212 offset:18432
	v_fmac_f32_e32 v2, v160, v1
	v_fmac_f32_e32 v34, v160, v33
	v_cvt_pk_bf16_f32 v213, v1, v33
	v_fma_f32 v2, -v161, v33, v2
	v_fmac_f32_e32 v34, v161, v1
	ds_write_b32 v185, v213 offset:18704
	v_fmac_f32_e32 v3, v160, v2
	v_fmac_f32_e32 v35, v160, v34
	v_cvt_pk_bf16_f32 v214, v2, v34
	v_fma_f32 v3, -v161, v34, v3
	v_fmac_f32_e32 v35, v161, v2
	ds_write_b32 v185, v214 offset:18976
	v_fmac_f32_e32 v16, v160, v3
	v_fmac_f32_e32 v196, v160, v35
	v_cvt_pk_bf16_f32 v215, v3, v35
	v_fma_f32 v16, -v161, v35, v16
	v_fmac_f32_e32 v196, v161, v3
	ds_write_b32 v185, v215 offset:19248
	v_fmac_f32_e32 v17, v160, v16
	v_fmac_f32_e32 v197, v160, v196
	v_cvt_pk_bf16_f32 v212, v16, v196
	v_fma_f32 v17, -v161, v196, v17
	v_fmac_f32_e32 v197, v161, v16
	ds_write_b32 v185, v212 offset:19520
	v_fmac_f32_e32 v18, v160, v17
	v_fmac_f32_e32 v198, v160, v197
	v_cvt_pk_bf16_f32 v213, v17, v197
	v_fma_f32 v18, -v161, v197, v18
	v_fmac_f32_e32 v198, v161, v17
	ds_write_b32 v185, v213 offset:19792
	v_fmac_f32_e32 v19, v160, v18
	v_fmac_f32_e32 v199, v160, v198
	v_cvt_pk_bf16_f32 v214, v18, v198
	v_fma_f32 v19, -v161, v198, v19
	v_fmac_f32_e32 v199, v161, v18
	ds_write_b32 v185, v214 offset:20064
	v_fmac_f32_e32 v4, v160, v19
	v_fmac_f32_e32 v36, v160, v199
	v_cvt_pk_bf16_f32 v215, v19, v199
	v_fma_f32 v4, -v161, v199, v4
	v_fmac_f32_e32 v36, v161, v19
	ds_write_b32 v185, v215 offset:20336
	v_fmac_f32_e32 v5, v160, v4
	v_fmac_f32_e32 v37, v160, v36
	v_cvt_pk_bf16_f32 v212, v4, v36
	v_fma_f32 v5, -v161, v36, v5
	v_fmac_f32_e32 v37, v161, v4
	ds_write_b32 v185, v212 offset:20608
	v_fmac_f32_e32 v6, v160, v5
	v_fmac_f32_e32 v38, v160, v37
	v_cvt_pk_bf16_f32 v213, v5, v37
	v_fma_f32 v6, -v161, v37, v6
	v_fmac_f32_e32 v38, v161, v5
	ds_write_b32 v185, v213 offset:20880
	v_fmac_f32_e32 v7, v160, v6
	v_fmac_f32_e32 v39, v160, v38
	v_cvt_pk_bf16_f32 v214, v6, v38
	v_fma_f32 v7, -v161, v38, v7
	v_fmac_f32_e32 v39, v161, v6
	ds_write_b32 v185, v214 offset:21152
	v_fmac_f32_e32 v20, v160, v7
	v_fmac_f32_e32 v200, v160, v39
	v_cvt_pk_bf16_f32 v215, v7, v39
	v_fma_f32 v20, -v161, v39, v20
	v_fmac_f32_e32 v200, v161, v7
	ds_write_b32 v185, v215 offset:21424
	v_fmac_f32_e32 v21, v160, v20
	v_fmac_f32_e32 v201, v160, v200
	v_cvt_pk_bf16_f32 v212, v20, v200
	v_fma_f32 v21, -v161, v200, v21
	v_fmac_f32_e32 v201, v161, v20
	ds_write_b32 v185, v212 offset:21696
	v_fmac_f32_e32 v22, v160, v21
	v_fmac_f32_e32 v202, v160, v201
	v_cvt_pk_bf16_f32 v213, v21, v201
	v_fma_f32 v22, -v161, v201, v22
	v_fmac_f32_e32 v202, v161, v21
	ds_write_b32 v185, v213 offset:21968
	v_fmac_f32_e32 v23, v160, v22
	v_fmac_f32_e32 v203, v160, v202
	v_cvt_pk_bf16_f32 v214, v22, v202
	v_fma_f32 v23, -v161, v202, v23
	v_fmac_f32_e32 v203, v161, v22
	ds_write_b32 v185, v214 offset:22240
	v_fmac_f32_e32 v8, v160, v23
	v_fmac_f32_e32 v40, v160, v203
	v_cvt_pk_bf16_f32 v215, v23, v203
	v_fma_f32 v8, -v161, v203, v8
	v_fmac_f32_e32 v40, v161, v23
	ds_write_b32 v185, v215 offset:22512
	v_fmac_f32_e32 v9, v160, v8
	v_fmac_f32_e32 v41, v160, v40
	v_cvt_pk_bf16_f32 v212, v8, v40
	v_fma_f32 v9, -v161, v40, v9
	v_fmac_f32_e32 v41, v161, v8
	ds_write_b32 v185, v212 offset:22784
	v_fmac_f32_e32 v10, v160, v9
	v_fmac_f32_e32 v42, v160, v41
	v_cvt_pk_bf16_f32 v213, v9, v41
	v_fma_f32 v10, -v161, v41, v10
	v_fmac_f32_e32 v42, v161, v9
	ds_write_b32 v185, v213 offset:23056
	v_fmac_f32_e32 v11, v160, v10
	v_fmac_f32_e32 v43, v160, v42
	v_cvt_pk_bf16_f32 v214, v10, v42
	v_fma_f32 v11, -v161, v42, v11
	v_fmac_f32_e32 v43, v161, v10
	ds_write_b32 v185, v214 offset:23328
	v_fmac_f32_e32 v24, v160, v11
	v_fmac_f32_e32 v204, v160, v43
	v_cvt_pk_bf16_f32 v215, v11, v43
	v_fma_f32 v24, -v161, v43, v24
	v_fmac_f32_e32 v204, v161, v11
	ds_write_b32 v185, v215 offset:23600
	v_fmac_f32_e32 v25, v160, v24
	v_fmac_f32_e32 v205, v160, v204
	v_cvt_pk_bf16_f32 v212, v24, v204
	v_fma_f32 v25, -v161, v204, v25
	v_fmac_f32_e32 v205, v161, v24
	ds_write_b32 v185, v212 offset:23872
	v_fmac_f32_e32 v26, v160, v25
	v_fmac_f32_e32 v206, v160, v205
	v_cvt_pk_bf16_f32 v213, v25, v205
	v_fma_f32 v26, -v161, v205, v26
	v_fmac_f32_e32 v206, v161, v25
	ds_write_b32 v185, v213 offset:24144
	v_fmac_f32_e32 v27, v160, v26
	v_fmac_f32_e32 v207, v160, v206
	v_cvt_pk_bf16_f32 v214, v26, v206
	v_fma_f32 v27, -v161, v206, v27
	v_fmac_f32_e32 v207, v161, v26
	ds_write_b32 v185, v214 offset:24416
	v_fmac_f32_e32 v12, v160, v27
	v_fmac_f32_e32 v44, v160, v207
	v_cvt_pk_bf16_f32 v215, v27, v207
	v_fma_f32 v12, -v161, v207, v12
	v_fmac_f32_e32 v44, v161, v27
	ds_write_b32 v185, v215 offset:24688
	v_fmac_f32_e32 v13, v160, v12
	v_fmac_f32_e32 v45, v160, v44
	v_cvt_pk_bf16_f32 v212, v12, v44
	v_fma_f32 v13, -v161, v44, v13
	v_fmac_f32_e32 v45, v161, v12
	ds_write_b32 v185, v212 offset:24960
	v_fmac_f32_e32 v14, v160, v13
	v_fmac_f32_e32 v46, v160, v45
	v_cvt_pk_bf16_f32 v213, v13, v45
	v_fma_f32 v14, -v161, v45, v14
	v_fmac_f32_e32 v46, v161, v13
	ds_write_b32 v185, v213 offset:25232
	v_fmac_f32_e32 v15, v160, v14
	v_fmac_f32_e32 v47, v160, v46
	v_cvt_pk_bf16_f32 v214, v14, v46
	v_fma_f32 v15, -v161, v46, v15
	v_fmac_f32_e32 v47, v161, v14
	ds_write_b32 v185, v214 offset:25504
	v_fmac_f32_e32 v28, v160, v15
	v_fmac_f32_e32 v208, v160, v47
	v_cvt_pk_bf16_f32 v215, v15, v47
	v_fma_f32 v28, -v161, v47, v28
	v_fmac_f32_e32 v208, v161, v15
	ds_write_b32 v185, v215 offset:25776
	v_fmac_f32_e32 v29, v160, v28
	v_fmac_f32_e32 v209, v160, v208
	v_cvt_pk_bf16_f32 v212, v28, v208
	v_fma_f32 v29, -v161, v208, v29
	v_fmac_f32_e32 v209, v161, v28
	ds_write_b32 v185, v212 offset:26048
	v_fmac_f32_e32 v30, v160, v29
	v_fmac_f32_e32 v210, v160, v209
	v_cvt_pk_bf16_f32 v213, v29, v209
	v_fma_f32 v30, -v161, v209, v30
	v_fmac_f32_e32 v210, v161, v29
	ds_write_b32 v185, v213 offset:26320
	v_fmac_f32_e32 v31, v160, v30
	v_fmac_f32_e32 v211, v160, v210
	v_cvt_pk_bf16_f32 v214, v30, v210
	v_fma_f32 v31, -v161, v210, v31
	v_fmac_f32_e32 v211, v161, v30
	ds_write_b32 v185, v214 offset:26592
	v_mov_b32_e32 v188, v31
	v_mov_b32_e32 v189, v211
	v_cvt_pk_bf16_f32 v215, v31, v211
	ds_write_b32 v185, v215 offset:26864
	s_waitcnt lgkmcnt(0)
	ds_read_b128 v[32:35], v186 offset:18432
	ds_read_b128 v[36:39], v186 offset:18464
	ds_read_b128 v[40:43], v186 offset:18496
	ds_read_b128 v[44:47], v186 offset:18528
	ds_read_b128 v[196:199], v186 offset:18560
	ds_read_b128 v[200:203], v186 offset:18592
	ds_read_b128 v[204:207], v186 offset:18624
	ds_read_b128 v[208:211], v186 offset:18656
	s_waitcnt lgkmcnt(7)
	v_mfma_f32_32x32x16_bf16 v[48:63], v[64:67], v[32:35], 0
	v_fmac_f32_e32 v234, v100, v162
	v_fmac_f32_e32 v235, v101, v163
	v_fmac_f32_e32 v236, v102, v164
	v_fmac_f32_e32 v237, v103, v165
	v_fmac_f32_e32 v238, v80, v166
	v_fmac_f32_e32 v239, v81, v167
	v_fmac_f32_e32 v240, v82, v192
	v_fmac_f32_e32 v241, v83, v193
	v_mul_f32_e32 v242, v234, v234
	s_waitcnt lgkmcnt(6)
	v_mfma_f32_32x32x16_bf16 v[48:63], v[68:71], v[36:39], v[48:63]
	v_mul_f32_e32 v243, v235, v235
	v_mul_f32_e32 v244, v236, v236
	v_mul_f32_e32 v245, v237, v237
	v_mul_f32_e32 v246, v238, v238
	v_mul_f32_e32 v247, v239, v239
	v_mul_f32_e32 v248, v240, v240
	v_mul_f32_e32 v249, v241, v241
	v_fmaak_f32 v242, v242, v184, 0xc0135761
	v_fmaak_f32 v243, v243, v184, 0xc0135761
	s_waitcnt lgkmcnt(5)
	v_mfma_f32_32x32x16_bf16 v[48:63], v[72:75], v[40:43], v[48:63]
	v_fmaak_f32 v244, v244, v184, 0xc0135761
	v_fmaak_f32 v245, v245, v184, 0xc0135761
	v_fmaak_f32 v246, v246, v184, 0xc0135761
	v_fmaak_f32 v247, v247, v184, 0xc0135761
	v_fmaak_f32 v248, v248, v184, 0xc0135761
	v_fmaak_f32 v249, v249, v184, 0xc0135761
	v_mul_f32_e32 v242, v234, v242
	v_mul_f32_e32 v243, v235, v243
	v_mul_f32_e32 v244, v236, v244
	s_waitcnt lgkmcnt(4)
	v_mfma_f32_32x32x16_bf16 v[48:63], v[76:79], v[44:47], v[48:63]
	v_mul_f32_e32 v245, v237, v245
	v_mul_f32_e32 v246, v238, v246
	v_mul_f32_e32 v247, v239, v247
	v_mul_f32_e32 v248, v240, v248
	v_mul_f32_e32 v249, v241, v249
	v_exp_f32_e32 v242, v242
	v_exp_f32_e32 v243, v243
	v_exp_f32_e32 v244, v244
	v_exp_f32_e32 v245, v245
	s_waitcnt lgkmcnt(3)
	v_mfma_f32_32x32x16_bf16 v[48:63], v[84:87], v[196:199], v[48:63]
	v_exp_f32_e32 v246, v246
	v_exp_f32_e32 v247, v247
	v_exp_f32_e32 v248, v248
	v_exp_f32_e32 v249, v249
	v_add_f32_e32 v242, 1.0, v242
	v_add_f32_e32 v243, 1.0, v243
	v_add_f32_e32 v244, 1.0, v244
	v_add_f32_e32 v245, 1.0, v245
	s_waitcnt lgkmcnt(2)
	v_mfma_f32_32x32x16_bf16 v[48:63], v[88:91], v[200:203], v[48:63]
	v_add_f32_e32 v246, 1.0, v246
	v_add_f32_e32 v247, 1.0, v247
	v_add_f32_e32 v248, 1.0, v248
	v_add_f32_e32 v249, 1.0, v249
	v_rcp_f32_e32 v242, v242
	v_rcp_f32_e32 v243, v243
	v_rcp_f32_e32 v244, v244
	v_rcp_f32_e32 v245, v245
	s_waitcnt lgkmcnt(1)
	v_mfma_f32_32x32x16_bf16 v[48:63], v[96:99], v[204:207], v[48:63]
	v_rcp_f32_e32 v246, v246
	v_rcp_f32_e32 v247, v247
	v_rcp_f32_e32 v248, v248
	v_rcp_f32_e32 v249, v249
	v_mul_f32_e32 v234, v234, v242
	v_mul_f32_e32 v235, v235, v243
	v_mul_f32_e32 v236, v236, v244
	v_mul_f32_e32 v237, v237, v245
	s_waitcnt lgkmcnt(0)
	v_mfma_f32_32x32x16_bf16 v[48:63], v[108:111], v[208:211], v[48:63]
	v_mul_f32_e32 v238, v238, v246
	v_mul_f32_e32 v239, v239, v247
	v_mul_f32_e32 v240, v240, v248
	v_mul_f32_e32 v241, v241, v249
	v_cvt_pk_bf16_f32 v242, v234, v235
	v_cvt_pk_bf16_f32 v243, v236, v237
	v_cvt_pk_bf16_f32 v244, v238, v239
	v_cvt_pk_bf16_f32 v245, v240, v241
	s_cmp_eq_u32 s16, 0x800
	s_cbranch_scc1 .Lscan_nostore
	global_store_dwordx2 v253, v[242:243], s[14:15]
	global_store_dwordx2 v254, v[244:245], s[14:15]
	s_movk_i32 s18, 0x1000
	s_and_b32 s17, s16, 0x3800
	s_cmp_eq_u32 s17, 0x800
	s_cselect_b32 s18, 0x1f9000, s18
	s_add_u32 s14, s14, s18
	s_addc_u32 s15, s15, 0

.Lscan_go_1:
	v_mfma_f32_32x32x16_bf16 v[0:15], v[168:171], v[104:107], 0
	s_addk_i32 s16, 0x800
	v_mfma_f32_32x32x16_bf16 v[16:31], v[168:171], v[116:119], 0
	v_mfma_f32_32x32x16_bf16 v[32:47], v[168:171], v[92:95], 0
	v_mfma_f32_32x32x16_bf16 v[196:211], v[168:171], v[112:115], 0
	v_mov_b32_e32 v218, v168
	v_mov_b32_e32 v219, v169
	v_mov_b32_e32 v220, v170
	v_mov_b32_e32 v221, v171
	s_nop 0
	v_permlane32_swap_b32_e32 v218, v220
	v_permlane32_swap_b32_e32 v219, v221
	s_add_u32 s0, s0, 0x40000
	s_addc_u32 s1, s1, 0
	v_lshl_add_u64 v[216:217], v[152:153], 0, s[0:1]
	global_load_dwordx4 v[168:171], v[216:217], off
	v_lshlrev_b32_e32 v162, 16, v218
	v_and_b32_e32 v163, 0xffff0000, v218
	v_lshlrev_b32_e32 v164, 16, v219
	v_and_b32_e32 v165, 0xffff0000, v219
	v_lshlrev_b32_e32 v166, 16, v220
	v_and_b32_e32 v167, 0xffff0000, v220
	v_lshlrev_b32_e32 v192, 16, v221
	v_and_b32_e32 v193, 0xffff0000, v221
	v_permlane32_swap_b32_e32 v0, v16
	v_permlane32_swap_b32_e32 v1, v17
	v_permlane32_swap_b32_e32 v2, v18
	v_permlane32_swap_b32_e32 v3, v19
	v_permlane32_swap_b32_e32 v4, v20
	v_permlane32_swap_b32_e32 v5, v21
	v_permlane32_swap_b32_e32 v6, v22
	v_permlane32_swap_b32_e32 v7, v23
	v_permlane32_swap_b32_e32 v8, v24
	v_permlane32_swap_b32_e32 v9, v25
	v_permlane32_swap_b32_e32 v10, v26
	v_permlane32_swap_b32_e32 v11, v27
	v_permlane32_swap_b32_e32 v12, v28
	v_permlane32_swap_b32_e32 v13, v29
	v_permlane32_swap_b32_e32 v14, v30
	v_permlane32_swap_b32_e32 v15, v31
	v_permlane32_swap_b32_e32 v32, v196
	v_permlane32_swap_b32_e32 v33, v197
	v_permlane32_swap_b32_e32 v34, v198
	v_permlane32_swap_b32_e32 v35, v199
	v_permlane32_swap_b32_e32 v36, v200
	v_permlane32_swap_b32_e32 v37, v201
	v_permlane32_swap_b32_e32 v38, v202
	v_permlane32_swap_b32_e32 v39, v203
	v_permlane32_swap_b32_e32 v40, v204
	v_permlane32_swap_b32_e32 v41, v205
	v_permlane32_swap_b32_e32 v42, v206
	v_permlane32_swap_b32_e32 v43, v207
	v_permlane32_swap_b32_e32 v44, v208
	v_permlane32_swap_b32_e32 v45, v209
	v_permlane32_swap_b32_e32 v46, v210
	v_permlane32_swap_b32_e32 v47, v211
	v_fmac_f32_e32 v0, v160, v188
	v_fmac_f32_e32 v32, v160, v189
	v_fma_f32 v0, -v161, v189, v0
	v_fmac_f32_e32 v32, v161, v188
	v_fmac_f32_e32 v1, v160, v0
	v_fmac_f32_e32 v33, v160, v32
	v_cvt_pk_bf16_f32 v212, v0, v32
	v_fma_f32 v1, -v161, v32, v1
	v_fmac_f32_e32 v33, v161, v0
	ds_write_b32 v185, v212 offset:18432
	v_fmac_f32_e32 v2, v160, v1
	v_fmac_f32_e32 v34, v160, v33
	v_cvt_pk_bf16_f32 v213, v1, v33
	v_fma_f32 v2, -v161, v33, v2
	v_fmac_f32_e32 v34, v161, v1
	ds_write_b32 v185, v213 offset:18704
	v_fmac_f32_e32 v3, v160, v2
	v_fmac_f32_e32 v35, v160, v34
	v_cvt_pk_bf16_f32 v214, v2, v34
	v_fma_f32 v3, -v161, v34, v3
	v_fmac_f32_e32 v35, v161, v2
	ds_write_b32 v185, v214 offset:18976
	v_fmac_f32_e32 v16, v160, v3
	v_fmac_f32_e32 v196, v160, v35
	v_cvt_pk_bf16_f32 v215, v3, v35
	v_fma_f32 v16, -v161, v35, v16
	v_fmac_f32_e32 v196, v161, v3
	ds_write_b32 v185, v215 offset:19248
	v_fmac_f32_e32 v17, v160, v16
	v_fmac_f32_e32 v197, v160, v196
	v_cvt_pk_bf16_f32 v212, v16, v196
	v_fma_f32 v17, -v161, v196, v17
	v_fmac_f32_e32 v197, v161, v16
	ds_write_b32 v185, v212 offset:19520
	v_fmac_f32_e32 v18, v160, v17
	v_fmac_f32_e32 v198, v160, v197
	v_cvt_pk_bf16_f32 v213, v17, v197
	v_fma_f32 v18, -v161, v197, v18
	v_fmac_f32_e32 v198, v161, v17
	ds_write_b32 v185, v213 offset:19792
	v_fmac_f32_e32 v19, v160, v18
	v_fmac_f32_e32 v199, v160, v198
	v_cvt_pk_bf16_f32 v214, v18, v198
	v_fma_f32 v19, -v161, v198, v19
	v_fmac_f32_e32 v199, v161, v18
	ds_write_b32 v185, v214 offset:20064
	v_fmac_f32_e32 v4, v160, v19
	v_fmac_f32_e32 v36, v160, v199
	v_cvt_pk_bf16_f32 v215, v19, v199
	v_fma_f32 v4, -v161, v199, v4
	v_fmac_f32_e32 v36, v161, v19
	ds_write_b32 v185, v215 offset:20336
	v_fmac_f32_e32 v5, v160, v4
	v_fmac_f32_e32 v37, v160, v36
	v_cvt_pk_bf16_f32 v212, v4, v36
	v_fma_f32 v5, -v161, v36, v5
	v_fmac_f32_e32 v37, v161, v4
	ds_write_b32 v185, v212 offset:20608
	v_fmac_f32_e32 v6, v160, v5
	v_fmac_f32_e32 v38, v160, v37
	v_cvt_pk_bf16_f32 v213, v5, v37
	v_fma_f32 v6, -v161, v37, v6
	v_fmac_f32_e32 v38, v161, v5
	ds_write_b32 v185, v213 offset:20880
	v_fmac_f32_e32 v7, v160, v6
	v_fmac_f32_e32 v39, v160, v38
	v_cvt_pk_bf16_f32 v214, v6, v38
	v_fma_f32 v7, -v161, v38, v7
	v_fmac_f32_e32 v39, v161, v6
	ds_write_b32 v185, v214 offset:21152
	v_fmac_f32_e32 v20, v160, v7
	v_fmac_f32_e32 v200, v160, v39
	v_cvt_pk_bf16_f32 v215, v7, v39
	v_fma_f32 v20, -v161, v39, v20
	v_fmac_f32_e32 v200, v161, v7
	ds_write_b32 v185, v215 offset:21424
	v_fmac_f32_e32 v21, v160, v20
	v_fmac_f32_e32 v201, v160, v200
	v_cvt_pk_bf16_f32 v212, v20, v200
	v_fma_f32 v21, -v161, v200, v21
	v_fmac_f32_e32 v201, v161, v20
	ds_write_b32 v185, v212 offset:21696
	v_fmac_f32_e32 v22, v160, v21
	v_fmac_f32_e32 v202, v160, v201
	v_cvt_pk_bf16_f32 v213, v21, v201
	v_fma_f32 v22, -v161, v201, v22
	v_fmac_f32_e32 v202, v161, v21
	ds_write_b32 v185, v213 offset:21968
	v_fmac_f32_e32 v23, v160, v22
	v_fmac_f32_e32 v203, v160, v202
	v_cvt_pk_bf16_f32 v214, v22, v202
	v_fma_f32 v23, -v161, v202, v23
	v_fmac_f32_e32 v203, v161, v22
	ds_write_b32 v185, v214 offset:22240
	v_fmac_f32_e32 v8, v160, v23
	v_fmac_f32_e32 v40, v160, v203
	v_cvt_pk_bf16_f32 v215, v23, v203
	v_fma_f32 v8, -v161, v203, v8
	v_fmac_f32_e32 v40, v161, v23
	ds_write_b32 v185, v215 offset:22512
	v_fmac_f32_e32 v9, v160, v8
	v_fmac_f32_e32 v41, v160, v40
	v_cvt_pk_bf16_f32 v212, v8, v40
	v_fma_f32 v9, -v161, v40, v9
	v_fmac_f32_e32 v41, v161, v8
	ds_write_b32 v185, v212 offset:22784
	v_fmac_f32_e32 v10, v160, v9
	v_fmac_f32_e32 v42, v160, v41
	v_cvt_pk_bf16_f32 v213, v9, v41
	v_fma_f32 v10, -v161, v41, v10
	v_fmac_f32_e32 v42, v161, v9
	ds_write_b32 v185, v213 offset:23056
	v_fmac_f32_e32 v11, v160, v10
	v_fmac_f32_e32 v43, v160, v42
	v_cvt_pk_bf16_f32 v214, v10, v42
	v_fma_f32 v11, -v161, v42, v11
	v_fmac_f32_e32 v43, v161, v10
	ds_write_b32 v185, v214 offset:23328
	v_fmac_f32_e32 v24, v160, v11
	v_fmac_f32_e32 v204, v160, v43
	v_cvt_pk_bf16_f32 v215, v11, v43
	v_fma_f32 v24, -v161, v43, v24
	v_fmac_f32_e32 v204, v161, v11
	ds_write_b32 v185, v215 offset:23600
	v_fmac_f32_e32 v25, v160, v24
	v_fmac_f32_e32 v205, v160, v204
	v_cvt_pk_bf16_f32 v212, v24, v204
	v_fma_f32 v25, -v161, v204, v25
	v_fmac_f32_e32 v205, v161, v24
	ds_write_b32 v185, v212 offset:23872
	v_fmac_f32_e32 v26, v160, v25
	v_fmac_f32_e32 v206, v160, v205
	v_cvt_pk_bf16_f32 v213, v25, v205
	v_fma_f32 v26, -v161, v205, v26
	v_fmac_f32_e32 v206, v161, v25
	ds_write_b32 v185, v213 offset:24144
	v_fmac_f32_e32 v27, v160, v26
	v_fmac_f32_e32 v207, v160, v206
	v_cvt_pk_bf16_f32 v214, v26, v206
	v_fma_f32 v27, -v161, v206, v27
	v_fmac_f32_e32 v207, v161, v26
	ds_write_b32 v185, v214 offset:24416
	v_fmac_f32_e32 v12, v160, v27
	v_fmac_f32_e32 v44, v160, v207
	v_cvt_pk_bf16_f32 v215, v27, v207
	v_fma_f32 v12, -v161, v207, v12
	v_fmac_f32_e32 v44, v161, v27
	ds_write_b32 v185, v215 offset:24688
	v_fmac_f32_e32 v13, v160, v12
	v_fmac_f32_e32 v45, v160, v44
	v_cvt_pk_bf16_f32 v212, v12, v44
	v_fma_f32 v13, -v161, v44, v13
	v_fmac_f32_e32 v45, v161, v12
	ds_write_b32 v185, v212 offset:24960
	v_fmac_f32_e32 v14, v160, v13
	v_fmac_f32_e32 v46, v160, v45
	v_cvt_pk_bf16_f32 v213, v13, v45
	v_fma_f32 v14, -v161, v45, v14
	v_fmac_f32_e32 v46, v161, v13
	ds_write_b32 v185, v213 offset:25232
	v_fmac_f32_e32 v15, v160, v14
	v_fmac_f32_e32 v47, v160, v46
	v_cvt_pk_bf16_f32 v214, v14, v46
	v_fma_f32 v15, -v161, v46, v15
	v_fmac_f32_e32 v47, v161, v14
	ds_write_b32 v185, v214 offset:25504
	v_fmac_f32_e32 v28, v160, v15
	v_fmac_f32_e32 v208, v160, v47
	v_cvt_pk_bf16_f32 v215, v15, v47
	v_fma_f32 v28, -v161, v47, v28
	v_fmac_f32_e32 v208, v161, v15
	ds_write_b32 v185, v215 offset:25776
	v_fmac_f32_e32 v29, v160, v28
	v_fmac_f32_e32 v209, v160, v208
	v_cvt_pk_bf16_f32 v212, v28, v208
	v_fma_f32 v29, -v161, v208, v29
	v_fmac_f32_e32 v209, v161, v28
	ds_write_b32 v185, v212 offset:26048
	v_fmac_f32_e32 v30, v160, v29
	v_fmac_f32_e32 v210, v160, v209
	v_cvt_pk_bf16_f32 v213, v29, v209
	v_fma_f32 v30, -v161, v209, v30
	v_fmac_f32_e32 v210, v161, v29
	ds_write_b32 v185, v213 offset:26320
	v_fmac_f32_e32 v31, v160, v30
	v_fmac_f32_e32 v211, v160, v210
	v_cvt_pk_bf16_f32 v214, v30, v210
	v_fma_f32 v31, -v161, v210, v31
	v_fmac_f32_e32 v211, v161, v30
	ds_write_b32 v185, v214 offset:26592
	v_mov_b32_e32 v188, v31
	v_mov_b32_e32 v189, v211
	v_cvt_pk_bf16_f32 v215, v31, v211
	ds_write_b32 v185, v215 offset:26864
	s_waitcnt lgkmcnt(0)
	ds_read_b128 v[32:35], v186 offset:18432
	ds_read_b128 v[36:39], v186 offset:18464
	ds_read_b128 v[40:43], v186 offset:18496
	ds_read_b128 v[44:47], v186 offset:18528
	ds_read_b128 v[196:199], v186 offset:18560
	ds_read_b128 v[200:203], v186 offset:18592
	ds_read_b128 v[204:207], v186 offset:18624
	ds_read_b128 v[208:211], v186 offset:18656
	s_waitcnt lgkmcnt(7)
	v_mfma_f32_32x32x16_bf16 v[234:249], v[64:67], v[32:35], 0
	v_fmac_f32_e32 v48, v100, v228
	v_fmac_f32_e32 v49, v101, v229
	v_fmac_f32_e32 v50, v102, v230
	v_fmac_f32_e32 v51, v103, v231
	v_fmac_f32_e32 v52, v80, v232
	v_fmac_f32_e32 v53, v81, v233
	v_fmac_f32_e32 v54, v82, v251
	v_fmac_f32_e32 v55, v83, v252
	v_mul_f32_e32 v56, v48, v48
	s_waitcnt lgkmcnt(6)
	v_mfma_f32_32x32x16_bf16 v[234:249], v[68:71], v[36:39], v[234:249]
	v_mul_f32_e32 v57, v49, v49
	v_mul_f32_e32 v58, v50, v50
	v_mul_f32_e32 v59, v51, v51
	v_mul_f32_e32 v60, v52, v52
	v_mul_f32_e32 v61, v53, v53
	v_mul_f32_e32 v62, v54, v54
	v_mul_f32_e32 v63, v55, v55
	v_fmaak_f32 v56, v56, v184, 0xc0135761
	v_fmaak_f32 v57, v57, v184, 0xc0135761
	s_waitcnt lgkmcnt(5)
	v_mfma_f32_32x32x16_bf16 v[234:249], v[72:75], v[40:43], v[234:249]
	v_fmaak_f32 v58, v58, v184, 0xc0135761
	v_fmaak_f32 v59, v59, v184, 0xc0135761
	v_fmaak_f32 v60, v60, v184, 0xc0135761
	v_fmaak_f32 v61, v61, v184, 0xc0135761
	v_fmaak_f32 v62, v62, v184, 0xc0135761
	v_fmaak_f32 v63, v63, v184, 0xc0135761
	v_mul_f32_e32 v56, v48, v56
	v_mul_f32_e32 v57, v49, v57
	v_mul_f32_e32 v58, v50, v58
	s_waitcnt lgkmcnt(4)
	v_mfma_f32_32x32x16_bf16 v[234:249], v[76:79], v[44:47], v[234:249]
	v_mul_f32_e32 v59, v51, v59
	v_mul_f32_e32 v60, v52, v60
	v_mul_f32_e32 v61, v53, v61
	v_mul_f32_e32 v62, v54, v62
	v_mul_f32_e32 v63, v55, v63
	v_exp_f32_e32 v56, v56
	v_exp_f32_e32 v57, v57
	v_exp_f32_e32 v58, v58
	v_exp_f32_e32 v59, v59
	s_waitcnt lgkmcnt(3)
	v_mfma_f32_32x32x16_bf16 v[234:249], v[84:87], v[196:199], v[234:249]
	v_exp_f32_e32 v60, v60
	v_exp_f32_e32 v61, v61
	v_exp_f32_e32 v62, v62
	v_exp_f32_e32 v63, v63
	v_add_f32_e32 v56, 1.0, v56
	v_add_f32_e32 v57, 1.0, v57
	v_add_f32_e32 v58, 1.0, v58
	v_add_f32_e32 v59, 1.0, v59
	s_waitcnt lgkmcnt(2)
	v_mfma_f32_32x32x16_bf16 v[234:249], v[88:91], v[200:203], v[234:249]
	v_add_f32_e32 v60, 1.0, v60
	v_add_f32_e32 v61, 1.0, v61
	v_add_f32_e32 v62, 1.0, v62
	v_add_f32_e32 v63, 1.0, v63
	v_rcp_f32_e32 v56, v56
	v_rcp_f32_e32 v57, v57
	v_rcp_f32_e32 v58, v58
	v_rcp_f32_e32 v59, v59
	s_waitcnt lgkmcnt(1)
	v_mfma_f32_32x32x16_bf16 v[234:249], v[96:99], v[204:207], v[234:249]
	v_rcp_f32_e32 v60, v60
	v_rcp_f32_e32 v61, v61
	v_rcp_f32_e32 v62, v62
	v_rcp_f32_e32 v63, v63
	v_mul_f32_e32 v48, v48, v56
	v_mul_f32_e32 v49, v49, v57
	v_mul_f32_e32 v50, v50, v58
	v_mul_f32_e32 v51, v51, v59
	s_waitcnt lgkmcnt(0)
	v_mfma_f32_32x32x16_bf16 v[234:249], v[108:111], v[208:211], v[234:249]
	v_mul_f32_e32 v52, v52, v60
	v_mul_f32_e32 v53, v53, v61
	v_mul_f32_e32 v54, v54, v62
	v_mul_f32_e32 v55, v55, v63
	v_cvt_pk_bf16_f32 v56, v48, v49
	v_cvt_pk_bf16_f32 v57, v50, v51
	v_cvt_pk_bf16_f32 v58, v52, v53
	v_cvt_pk_bf16_f32 v59, v54, v55
	global_store_dwordx2 v253, v[56:57], s[14:15]
	global_store_dwordx2 v254, v[58:59], s[14:15]
	s_movk_i32 s18, 0x1000
	s_and_b32 s17, s16, 0x3800
	s_cmp_eq_u32 s17, 0x800
	s_cselect_b32 s18, 0x1f9000, s18
	s_add_u32 s14, s14, s18
	s_addc_u32 s15, s15, 0
	s_cmp_lt_u32 s16, 0x2800
	s_cbranch_scc1 .Lscan_w3_2
	s_waitcnt vmcnt(11)
.Lscan_go_2:
	v_mfma_f32_32x32x16_bf16 v[0:15], v[156:159], v[104:107], 0
	s_addk_i32 s16, 0x800
	v_mfma_f32_32x32x16_bf16 v[16:31], v[156:159], v[116:119], 0
	v_mfma_f32_32x32x16_bf16 v[32:47], v[156:159], v[92:95], 0
	v_mfma_f32_32x32x16_bf16 v[196:211], v[156:159], v[112:115], 0
	v_mov_b32_e32 v218, v156
	v_mov_b32_e32 v219, v157
	v_mov_b32_e32 v220, v158
	v_mov_b32_e32 v221, v159
	s_nop 0
	v_permlane32_swap_b32_e32 v218, v220
	v_permlane32_swap_b32_e32 v219, v221
	s_add_u32 s0, s0, 0x40000
	s_addc_u32 s1, s1, 0
	v_lshl_add_u64 v[216:217], v[152:153], 0, s[0:1]
	global_load_dwordx4 v[156:159], v[216:217], off
	v_lshlrev_b32_e32 v228, 16, v218
	v_and_b32_e32 v229, 0xffff0000, v218
	v_lshlrev_b32_e32 v230, 16, v219
	v_and_b32_e32 v231, 0xffff0000, v219
	v_lshlrev_b32_e32 v232, 16, v220
	v_and_b32_e32 v233, 0xffff0000, v220
	v_lshlrev_b32_e32 v251, 16, v221
	v_and_b32_e32 v252, 0xffff0000, v221
	v_permlane32_swap_b32_e32 v0, v16
	v_permlane32_swap_b32_e32 v1, v17
	v_permlane32_swap_b32_e32 v2, v18
	v_permlane32_swap_b32_e32 v3, v19
	v_permlane32_swap_b32_e32 v4, v20
	v_permlane32_swap_b32_e32 v5, v21
	v_permlane32_swap_b32_e32 v6, v22
	v_permlane32_swap_b32_e32 v7, v23
	v_permlane32_swap_b32_e32 v8, v24
	v_permlane32_swap_b32_e32 v9, v25
	v_permlane32_swap_b32_e32 v10, v26
	v_permlane32_swap_b32_e32 v11, v27
	v_permlane32_swap_b32_e32 v12, v28
	v_permlane32_swap_b32_e32 v13, v29
	v_permlane32_swap_b32_e32 v14, v30
	v_permlane32_swap_b32_e32 v15, v31
	v_permlane32_swap_b32_e32 v32, v196
	v_permlane32_swap_b32_e32 v33, v197
	v_permlane32_swap_b32_e32 v34, v198
	v_permlane32_swap_b32_e32 v35, v199
	v_permlane32_swap_b32_e32 v36, v200
	v_permlane32_swap_b32_e32 v37, v201
	v_permlane32_swap_b32_e32 v38, v202
	v_permlane32_swap_b32_e32 v39, v203
	v_permlane32_swap_b32_e32 v40, v204
	v_permlane32_swap_b32_e32 v41, v205
	v_permlane32_swap_b32_e32 v42, v206
	v_permlane32_swap_b32_e32 v43, v207
	v_permlane32_swap_b32_e32 v44, v208
	v_permlane32_swap_b32_e32 v45, v209
	v_permlane32_swap_b32_e32 v46, v210
	v_permlane32_swap_b32_e32 v47, v211
	v_fmac_f32_e32 v0, v160, v188
	v_fmac_f32_e32 v32, v160, v189
	v_fma_f32 v0, -v161, v189, v0
	v_fmac_f32_e32 v32, v161, v188
	v_fmac_f32_e32 v1, v160, v0
	v_fmac_f32_e32 v33, v160, v32
	v_cvt_pk_bf16_f32 v212, v0, v32
	v_fma_f32 v1, -v161, v32, v1
	v_fmac_f32_e32 v33, v161, v0
	ds_write_b32 v185, v212 offset:18432
	v_fmac_f32_e32 v2, v160, v1
	v_fmac_f32_e32 v34, v160, v33
	v_cvt_pk_bf16_f32 v213, v1, v33
	v_fma_f32 v2, -v161, v33, v2
	v_fmac_f32_e32 v34, v161, v1
	ds_write_b32 v185, v213 offset:18704
	v_fmac_f32_e32 v3, v160, v2
	v_fmac_f32_e32 v35, v160, v34
	v_cvt_pk_bf16_f32 v214, v2, v34
	v_fma_f32 v3, -v161, v34, v3
	v_fmac_f32_e32 v35, v161, v2
	ds_write_b32 v185, v214 offset:18976
	v_fmac_f32_e32 v16, v160, v3
	v_fmac_f32_e32 v196, v160, v35
	v_cvt_pk_bf16_f32 v215, v3, v35
	v_fma_f32 v16, -v161, v35, v16
	v_fmac_f32_e32 v196, v161, v3
	ds_write_b32 v185, v215 offset:19248
	v_fmac_f32_e32 v17, v160, v16
	v_fmac_f32_e32 v197, v160, v196
	v_cvt_pk_bf16_f32 v212, v16, v196
	v_fma_f32 v17, -v161, v196, v17
	v_fmac_f32_e32 v197, v161, v16
	ds_write_b32 v185, v212 offset:19520
	v_fmac_f32_e32 v18, v160, v17
	v_fmac_f32_e32 v198, v160, v197
	v_cvt_pk_bf16_f32 v213, v17, v197
	v_fma_f32 v18, -v161, v197, v18
	v_fmac_f32_e32 v198, v161, v17
	ds_write_b32 v185, v213 offset:19792
	v_fmac_f32_e32 v19, v160, v18
	v_fmac_f32_e32 v199, v160, v198
	v_cvt_pk_bf16_f32 v214, v18, v198
	v_fma_f32 v19, -v161, v198, v19
	v_fmac_f32_e32 v199, v161, v18
	ds_write_b32 v185, v214 offset:20064
	v_fmac_f32_e32 v4, v160, v19
	v_fmac_f32_e32 v36, v160, v199
	v_cvt_pk_bf16_f32 v215, v19, v199
	v_fma_f32 v4, -v161, v199, v4
	v_fmac_f32_e32 v36, v161, v19
	ds_write_b32 v185, v215 offset:20336
	v_fmac_f32_e32 v5, v160, v4
	v_fmac_f32_e32 v37, v160, v36
	v_cvt_pk_bf16_f32 v212, v4, v36
	v_fma_f32 v5, -v161, v36, v5
	v_fmac_f32_e32 v37, v161, v4
	ds_write_b32 v185, v212 offset:20608
	v_fmac_f32_e32 v6, v160, v5
	v_fmac_f32_e32 v38, v160, v37
	v_cvt_pk_bf16_f32 v213, v5, v37
	v_fma_f32 v6, -v161, v37, v6
	v_fmac_f32_e32 v38, v161, v5
	ds_write_b32 v185, v213 offset:20880
	v_fmac_f32_e32 v7, v160, v6
	v_fmac_f32_e32 v39, v160, v38
	v_cvt_pk_bf16_f32 v214, v6, v38
	v_fma_f32 v7, -v161, v38, v7
	v_fmac_f32_e32 v39, v161, v6
	ds_write_b32 v185, v214 offset:21152
	v_fmac_f32_e32 v20, v160, v7
	v_fmac_f32_e32 v200, v160, v39
	v_cvt_pk_bf16_f32 v215, v7, v39
	v_fma_f32 v20, -v161, v39, v20
	v_fmac_f32_e32 v200, v161, v7
	ds_write_b32 v185, v215 offset:21424
	v_fmac_f32_e32 v21, v160, v20
	v_fmac_f32_e32 v201, v160, v200
	v_cvt_pk_bf16_f32 v212, v20, v200
	v_fma_f32 v21, -v161, v200, v21
	v_fmac_f32_e32 v201, v161, v20
	ds_write_b32 v185, v212 offset:21696
	v_fmac_f32_e32 v22, v160, v21
	v_fmac_f32_e32 v202, v160, v201
	v_cvt_pk_bf16_f32 v213, v21, v201
	v_fma_f32 v22, -v161, v201, v22
	v_fmac_f32_e32 v202, v161, v21
	ds_write_b32 v185, v213 offset:21968
	v_fmac_f32_e32 v23, v160, v22
	v_fmac_f32_e32 v203, v160, v202
	v_cvt_pk_bf16_f32 v214, v22, v202
	v_fma_f32 v23, -v161, v202, v23
	v_fmac_f32_e32 v203, v161, v22
	ds_write_b32 v185, v214 offset:22240
	v_fmac_f32_e32 v8, v160, v23
	v_fmac_f32_e32 v40, v160, v203
	v_cvt_pk_bf16_f32 v215, v23, v203
	v_fma_f32 v8, -v161, v203, v8
	v_fmac_f32_e32 v40, v161, v23
	ds_write_b32 v185, v215 offset:22512
	v_fmac_f32_e32 v9, v160, v8
	v_fmac_f32_e32 v41, v160, v40
	v_cvt_pk_bf16_f32 v212, v8, v40
	v_fma_f32 v9, -v161, v40, v9
	v_fmac_f32_e32 v41, v161, v8
	ds_write_b32 v185, v212 offset:22784
	v_fmac_f32_e32 v10, v160, v9
	v_fmac_f32_e32 v42, v160, v41
	v_cvt_pk_bf16_f32 v213, v9, v41
	v_fma_f32 v10, -v161, v41, v10
	v_fmac_f32_e32 v42, v161, v9
	ds_write_b32 v185, v213 offset:23056
	v_fmac_f32_e32 v11, v160, v10
	v_fmac_f32_e32 v43, v160, v42
	v_cvt_pk_bf16_f32 v214, v10, v42
	v_fma_f32 v11, -v161, v42, v11
	v_fmac_f32_e32 v43, v161, v10
	ds_write_b32 v185, v214 offset:23328
	v_fmac_f32_e32 v24, v160, v11
	v_fmac_f32_e32 v204, v160, v43
	v_cvt_pk_bf16_f32 v215, v11, v43
	v_fma_f32 v24, -v161, v43, v24
	v_fmac_f32_e32 v204, v161, v11
	ds_write_b32 v185, v215 offset:23600
	v_fmac_f32_e32 v25, v160, v24
	v_fmac_f32_e32 v205, v160, v204
	v_cvt_pk_bf16_f32 v212, v24, v204
	v_fma_f32 v25, -v161, v204, v25
	v_fmac_f32_e32 v205, v161, v24
	ds_write_b32 v185, v212 offset:23872
	v_fmac_f32_e32 v26, v160, v25
	v_fmac_f32_e32 v206, v160, v205
	v_cvt_pk_bf16_f32 v213, v25, v205
	v_fma_f32 v26, -v161, v205, v26
	v_fmac_f32_e32 v206, v161, v25
	ds_write_b32 v185, v213 offset:24144
	v_fmac_f32_e32 v27, v160, v26
	v_fmac_f32_e32 v207, v160, v206
	v_cvt_pk_bf16_f32 v214, v26, v206
	v_fma_f32 v27, -v161, v206, v27
	v_fmac_f32_e32 v207, v161, v26
	ds_write_b32 v185, v214 offset:24416
	v_fmac_f32_e32 v12, v160, v27
	v_fmac_f32_e32 v44, v160, v207
	v_cvt_pk_bf16_f32 v215, v27, v207
	v_fma_f32 v12, -v161, v207, v12
	v_fmac_f32_e32 v44, v161, v27
	ds_write_b32 v185, v215 offset:24688
	v_fmac_f32_e32 v13, v160, v12
	v_fmac_f32_e32 v45, v160, v44
	v_cvt_pk_bf16_f32 v212, v12, v44
	v_fma_f32 v13, -v161, v44, v13
	v_fmac_f32_e32 v45, v161, v12
	ds_write_b32 v185, v212 offset:24960
	v_fmac_f32_e32 v14, v160, v13
	v_fmac_f32_e32 v46, v160, v45
	v_cvt_pk_bf16_f32 v213, v13, v45
	v_fma_f32 v14, -v161, v45, v14
	v_fmac_f32_e32 v46, v161, v13
	ds_write_b32 v185, v213 offset:25232
	v_fmac_f32_e32 v15, v160, v14
	v_fmac_f32_e32 v47, v160, v46
	v_cvt_pk_bf16_f32 v214, v14, v46
	v_fma_f32 v15, -v161, v46, v15
	v_fmac_f32_e32 v47, v161, v14
	ds_write_b32 v185, v214 offset:25504
	v_fmac_f32_e32 v28, v160, v15
	v_fmac_f32_e32 v208, v160, v47
	v_cvt_pk_bf16_f32 v215, v15, v47
	v_fma_f32 v28, -v161, v47, v28
	v_fmac_f32_e32 v208, v161, v15
	ds_write_b32 v185, v215 offset:25776
	v_fmac_f32_e32 v29, v160, v28
	v_fmac_f32_e32 v209, v160, v208
	v_cvt_pk_bf16_f32 v212, v28, v208
	v_fma_f32 v29, -v161, v208, v29
	v_fmac_f32_e32 v209, v161, v28
	ds_write_b32 v185, v212 offset:26048
	v_fmac_f32_e32 v30, v160, v29
	v_fmac_f32_e32 v210, v160, v209
	v_cvt_pk_bf16_f32 v213, v29, v209
	v_fma_f32 v30, -v161, v209, v30
	v_fmac_f32_e32 v210, v161, v29
	ds_write_b32 v185, v213 offset:26320
	v_fmac_f32_e32 v31, v160, v30
	v_fmac_f32_e32 v211, v160, v210
	v_cvt_pk_bf16_f32 v214, v30, v210
	v_fma_f32 v31, -v161, v210, v31
	v_fmac_f32_e32 v211, v161, v30
	ds_write_b32 v185, v214 offset:26592
	v_mov_b32_e32 v188, v31
	v_mov_b32_e32 v189, v211
	v_cvt_pk_bf16_f32 v215, v31, v211
	ds_write_b32 v185, v215 offset:26864
	s_waitcnt lgkmcnt(0)
	ds_read_b128 v[32:35], v186 offset:18432
	ds_read_b128 v[36:39], v186 offset:18464
	ds_read_b128 v[40:43], v186 offset:18496
	ds_read_b128 v[44:47], v186 offset:18528
	ds_read_b128 v[196:199], v186 offset:18560
	ds_read_b128 v[200:203], v186 offset:18592
	ds_read_b128 v[204:207], v186 offset:18624
	ds_read_b128 v[208:211], v186 offset:18656
	s_waitcnt lgkmcnt(7)
	v_mfma_f32_32x32x16_bf16 v[48:63], v[64:67], v[32:35], 0
	v_fmac_f32_e32 v234, v100, v162
	v_fmac_f32_e32 v235, v101, v163
	v_fmac_f32_e32 v236, v102, v164
	v_fmac_f32_e32 v237, v103, v165
	v_fmac_f32_e32 v238, v80, v166
	v_fmac_f32_e32 v239, v81, v167
	v_fmac_f32_e32 v240, v82, v192
	v_fmac_f32_e32 v241, v83, v193
	v_mul_f32_e32 v242, v234, v234
	s_waitcnt lgkmcnt(6)
	v_mfma_f32_32x32x16_bf16 v[48:63], v[68:71], v[36:39], v[48:63]
	v_mul_f32_e32 v243, v235, v235
	v_mul_f32_e32 v244, v236, v236
	v_mul_f32_e32 v245, v237, v237
	v_mul_f32_e32 v246, v238, v238
	v_mul_f32_e32 v247, v239, v239
	v_mul_f32_e32 v248, v240, v240
	v_mul_f32_e32 v249, v241, v241
	v_fmaak_f32 v242, v242, v184, 0xc0135761
	v_fmaak_f32 v243, v243, v184, 0xc0135761
	s_waitcnt lgkmcnt(5)
	v_mfma_f32_32x32x16_bf16 v[48:63], v[72:75], v[40:43], v[48:63]
	v_fmaak_f32 v244, v244, v184, 0xc0135761
	v_fmaak_f32 v245, v245, v184, 0xc0135761
	v_fmaak_f32 v246, v246, v184, 0xc0135761
	v_fmaak_f32 v247, v247, v184, 0xc0135761
	v_fmaak_f32 v248, v248, v184, 0xc0135761
	v_fmaak_f32 v249, v249, v184, 0xc0135761
	v_mul_f32_e32 v242, v234, v242
	v_mul_f32_e32 v243, v235, v243
	v_mul_f32_e32 v244, v236, v244
	s_waitcnt lgkmcnt(4)
	v_mfma_f32_32x32x16_bf16 v[48:63], v[76:79], v[44:47], v[48:63]
	v_mul_f32_e32 v245, v237, v245
	v_mul_f32_e32 v246, v238, v246
	v_mul_f32_e32 v247, v239, v247
	v_mul_f32_e32 v248, v240, v248
	v_mul_f32_e32 v249, v241, v249
	v_exp_f32_e32 v242, v242
	v_exp_f32_e32 v243, v243
	v_exp_f32_e32 v244, v244
	v_exp_f32_e32 v245, v245
	s_waitcnt lgkmcnt(3)
	v_mfma_f32_32x32x16_bf16 v[48:63], v[84:87], v[196:199], v[48:63]
	v_exp_f32_e32 v246, v246
	v_exp_f32_e32 v247, v247
	v_exp_f32_e32 v248, v248
	v_exp_f32_e32 v249, v249
	v_add_f32_e32 v242, 1.0, v242
	v_add_f32_e32 v243, 1.0, v243
	v_add_f32_e32 v244, 1.0, v244
	v_add_f32_e32 v245, 1.0, v245
	s_waitcnt lgkmcnt(2)
	v_mfma_f32_32x32x16_bf16 v[48:63], v[88:91], v[200:203], v[48:63]
	v_add_f32_e32 v246, 1.0, v246
	v_add_f32_e32 v247, 1.0, v247
	v_add_f32_e32 v248, 1.0, v248
	v_add_f32_e32 v249, 1.0, v249
	v_rcp_f32_e32 v242, v242
	v_rcp_f32_e32 v243, v243
	v_rcp_f32_e32 v244, v244
	v_rcp_f32_e32 v245, v245
	s_waitcnt lgkmcnt(1)
	v_mfma_f32_32x32x16_bf16 v[48:63], v[96:99], v[204:207], v[48:63]
	v_rcp_f32_e32 v246, v246
	v_rcp_f32_e32 v247, v247
	v_rcp_f32_e32 v248, v248
	v_rcp_f32_e32 v249, v249
	v_mul_f32_e32 v234, v234, v242
	v_mul_f32_e32 v235, v235, v243
	v_mul_f32_e32 v236, v236, v244
	v_mul_f32_e32 v237, v237, v245
	s_waitcnt lgkmcnt(0)
	v_mfma_f32_32x32x16_bf16 v[48:63], v[108:111], v[208:211], v[48:63]
	v_mul_f32_e32 v238, v238, v246
	v_mul_f32_e32 v239, v239, v247
	v_mul_f32_e32 v240, v240, v248
	v_mul_f32_e32 v241, v241, v249
	v_cvt_pk_bf16_f32 v242, v234, v235
	v_cvt_pk_bf16_f32 v243, v236, v237
	v_cvt_pk_bf16_f32 v244, v238, v239
	v_cvt_pk_bf16_f32 v245, v240, v241
	global_store_dwordx2 v253, v[242:243], s[14:15]
	global_store_dwordx2 v254, v[244:245], s[14:15]
	s_movk_i32 s18, 0x1000
	s_and_b32 s17, s16, 0x3800
	s_cmp_eq_u32 s17, 0x800
	s_cselect_b32 s18, 0x1f9000, s18
	s_add_u32 s14, s14, s18
	s_addc_u32 s15, s15, 0
	s_cmp_lt_u32 s16, 0x2800
	s_cbranch_scc1 .Lscan_w3_3
	s_waitcnt vmcnt(11)
.Lscan_go_3:
	v_mfma_f32_32x32x16_bf16 v[0:15], v[178:181], v[104:107], 0
	s_addk_i32 s16, 0x800
	v_mfma_f32_32x32x16_bf16 v[16:31], v[178:181], v[116:119], 0
	v_mfma_f32_32x32x16_bf16 v[32:47], v[178:181], v[92:95], 0
	v_mfma_f32_32x32x16_bf16 v[196:211], v[178:181], v[112:115], 0
	v_mov_b32_e32 v218, v178
	v_mov_b32_e32 v219, v179
	v_mov_b32_e32 v220, v180
	v_mov_b32_e32 v221, v181
	s_nop 0
	v_permlane32_swap_b32_e32 v218, v220
	v_permlane32_swap_b32_e32 v219, v221
	s_add_u32 s0, s0, 0x40000
	s_addc_u32 s1, s1, 0
	v_lshl_add_u64 v[216:217], v[152:153], 0, s[0:1]
	global_load_dwordx4 v[178:181], v[216:217], off
	v_lshlrev_b32_e32 v162, 16, v218
	v_and_b32_e32 v163, 0xffff0000, v218
	v_lshlrev_b32_e32 v164, 16, v219
	v_and_b32_e32 v165, 0xffff0000, v219
	v_lshlrev_b32_e32 v166, 16, v220
	v_and_b32_e32 v167, 0xffff0000, v220
	v_lshlrev_b32_e32 v192, 16, v221
	v_and_b32_e32 v193, 0xffff0000, v221
	v_permlane32_swap_b32_e32 v0, v16
	v_permlane32_swap_b32_e32 v1, v17
	v_permlane32_swap_b32_e32 v2, v18
	v_permlane32_swap_b32_e32 v3, v19
	v_permlane32_swap_b32_e32 v4, v20
	v_permlane32_swap_b32_e32 v5, v21
	v_permlane32_swap_b32_e32 v6, v22
	v_permlane32_swap_b32_e32 v7, v23
	v_permlane32_swap_b32_e32 v8, v24
	v_permlane32_swap_b32_e32 v9, v25
	v_permlane32_swap_b32_e32 v10, v26
	v_permlane32_swap_b32_e32 v11, v27
	v_permlane32_swap_b32_e32 v12, v28
	v_permlane32_swap_b32_e32 v13, v29
	v_permlane32_swap_b32_e32 v14, v30
	v_permlane32_swap_b32_e32 v15, v31
	v_permlane32_swap_b32_e32 v32, v196
	v_permlane32_swap_b32_e32 v33, v197
	v_permlane32_swap_b32_e32 v34, v198
	v_permlane32_swap_b32_e32 v35, v199
	v_permlane32_swap_b32_e32 v36, v200
	v_permlane32_swap_b32_e32 v37, v201
	v_permlane32_swap_b32_e32 v38, v202
	v_permlane32_swap_b32_e32 v39, v203
	v_permlane32_swap_b32_e32 v40, v204
	v_permlane32_swap_b32_e32 v41, v205
	v_permlane32_swap_b32_e32 v42, v206
	v_permlane32_swap_b32_e32 v43, v207
	v_permlane32_swap_b32_e32 v44, v208
	v_permlane32_swap_b32_e32 v45, v209
	v_permlane32_swap_b32_e32 v46, v210
	v_permlane32_swap_b32_e32 v47, v211
	v_fmac_f32_e32 v0, v160, v188
	v_fmac_f32_e32 v32, v160, v189
	v_fma_f32 v0, -v161, v189, v0
	v_fmac_f32_e32 v32, v161, v188
	v_fmac_f32_e32 v1, v160, v0
	v_fmac_f32_e32 v33, v160, v32
	v_cvt_pk_bf16_f32 v212, v0, v32
	v_fma_f32 v1, -v161, v32, v1
	v_fmac_f32_e32 v33, v161, v0
	ds_write_b32 v185, v212 offset:18432
	v_fmac_f32_e32 v2, v160, v1
	v_fmac_f32_e32 v34, v160, v33
	v_cvt_pk_bf16_f32 v213, v1, v33
	v_fma_f32 v2, -v161, v33, v2
	v_fmac_f32_e32 v34, v161, v1
	ds_write_b32 v185, v213 offset:18704
	v_fmac_f32_e32 v3, v160, v2
	v_fmac_f32_e32 v35, v160, v34
	v_cvt_pk_bf16_f32 v214, v2, v34
	v_fma_f32 v3, -v161, v34, v3
	v_fmac_f32_e32 v35, v161, v2
	ds_write_b32 v185, v214 offset:18976
	v_fmac_f32_e32 v16, v160, v3
	v_fmac_f32_e32 v196, v160, v35
	v_cvt_pk_bf16_f32 v215, v3, v35
	v_fma_f32 v16, -v161, v35, v16
	v_fmac_f32_e32 v196, v161, v3
	ds_write_b32 v185, v215 offset:19248
	v_fmac_f32_e32 v17, v160, v16
	v_fmac_f32_e32 v197, v160, v196
	v_cvt_pk_bf16_f32 v212, v16, v196
	v_fma_f32 v17, -v161, v196, v17
	v_fmac_f32_e32 v197, v161, v16
	ds_write_b32 v185, v212 offset:19520
	v_fmac_f32_e32 v18, v160, v17
	v_fmac_f32_e32 v198, v160, v197
	v_cvt_pk_bf16_f32 v213, v17, v197
	v_fma_f32 v18, -v161, v197, v18
	v_fmac_f32_e32 v198, v161, v17
	ds_write_b32 v185, v213 offset:19792
	v_fmac_f32_e32 v19, v160, v18
	v_fmac_f32_e32 v199, v160, v198
	v_cvt_pk_bf16_f32 v214, v18, v198
	v_fma_f32 v19, -v161, v198, v19
	v_fmac_f32_e32 v199, v161, v18
	ds_write_b32 v185, v214 offset:20064
	v_fmac_f32_e32 v4, v160, v19
	v_fmac_f32_e32 v36, v160, v199
	v_cvt_pk_bf16_f32 v215, v19, v199
	v_fma_f32 v4, -v161, v199, v4
	v_fmac_f32_e32 v36, v161, v19
	ds_write_b32 v185, v215 offset:20336
	v_fmac_f32_e32 v5, v160, v4
	v_fmac_f32_e32 v37, v160, v36
	v_cvt_pk_bf16_f32 v212, v4, v36
	v_fma_f32 v5, -v161, v36, v5
	v_fmac_f32_e32 v37, v161, v4
	ds_write_b32 v185, v212 offset:20608
	v_fmac_f32_e32 v6, v160, v5
	v_fmac_f32_e32 v38, v160, v37
	v_cvt_pk_bf16_f32 v213, v5, v37
	v_fma_f32 v6, -v161, v37, v6
	v_fmac_f32_e32 v38, v161, v5
	ds_write_b32 v185, v213 offset:20880
	v_fmac_f32_e32 v7, v160, v6
	v_fmac_f32_e32 v39, v160, v38
	v_cvt_pk_bf16_f32 v214, v6, v38
	v_fma_f32 v7, -v161, v38, v7
	v_fmac_f32_e32 v39, v161, v6
	ds_write_b32 v185, v214 offset:21152
	v_fmac_f32_e32 v20, v160, v7
	v_fmac_f32_e32 v200, v160, v39
	v_cvt_pk_bf16_f32 v215, v7, v39
	v_fma_f32 v20, -v161, v39, v20
	v_fmac_f32_e32 v200, v161, v7
	ds_write_b32 v185, v215 offset:21424
	v_fmac_f32_e32 v21, v160, v20
	v_fmac_f32_e32 v201, v160, v200
	v_cvt_pk_bf16_f32 v212, v20, v200
	v_fma_f32 v21, -v161, v200, v21
	v_fmac_f32_e32 v201, v161, v20
	ds_write_b32 v185, v212 offset:21696
	v_fmac_f32_e32 v22, v160, v21
	v_fmac_f32_e32 v202, v160, v201
	v_cvt_pk_bf16_f32 v213, v21, v201
	v_fma_f32 v22, -v161, v201, v22
	v_fmac_f32_e32 v202, v161, v21
	ds_write_b32 v185, v213 offset:21968
	v_fmac_f32_e32 v23, v160, v22
	v_fmac_f32_e32 v203, v160, v202
	v_cvt_pk_bf16_f32 v214, v22, v202
	v_fma_f32 v23, -v161, v202, v23
	v_fmac_f32_e32 v203, v161, v22
	ds_write_b32 v185, v214 offset:22240
	v_fmac_f32_e32 v8, v160, v23
	v_fmac_f32_e32 v40, v160, v203
	v_cvt_pk_bf16_f32 v215, v23, v203
	v_fma_f32 v8, -v161, v203, v8
	v_fmac_f32_e32 v40, v161, v23
	ds_write_b32 v185, v215 offset:22512
	v_fmac_f32_e32 v9, v160, v8
	v_fmac_f32_e32 v41, v160, v40
	v_cvt_pk_bf16_f32 v212, v8, v40
	v_fma_f32 v9, -v161, v40, v9
	v_fmac_f32_e32 v41, v161, v8
	ds_write_b32 v185, v212 offset:22784
	v_fmac_f32_e32 v10, v160, v9
	v_fmac_f32_e32 v42, v160, v41
	v_cvt_pk_bf16_f32 v213, v9, v41
	v_fma_f32 v10, -v161, v41, v10
	v_fmac_f32_e32 v42, v161, v9
	ds_write_b32 v185, v213 offset:23056
	v_fmac_f32_e32 v11, v160, v10
	v_fmac_f32_e32 v43, v160, v42
	v_cvt_pk_bf16_f32 v214, v10, v42
	v_fma_f32 v11, -v161, v42, v11
	v_fmac_f32_e32 v43, v161, v10
	ds_write_b32 v185, v214 offset:23328
	v_fmac_f32_e32 v24, v160, v11
	v_fmac_f32_e32 v204, v160, v43
	v_cvt_pk_bf16_f32 v215, v11, v43
	v_fma_f32 v24, -v161, v43, v24
	v_fmac_f32_e32 v204, v161, v11
	ds_write_b32 v185, v215 offset:23600
	v_fmac_f32_e32 v25, v160, v24
	v_fmac_f32_e32 v205, v160, v204
	v_cvt_pk_bf16_f32 v212, v24, v204
	v_fma_f32 v25, -v161, v204, v25
	v_fmac_f32_e32 v205, v161, v24
	ds_write_b32 v185, v212 offset:23872
	v_fmac_f32_e32 v26, v160, v25
	v_fmac_f32_e32 v206, v160, v205
	v_cvt_pk_bf16_f32 v213, v25, v205
	v_fma_f32 v26, -v161, v205, v26
	v_fmac_f32_e32 v206, v161, v25
	ds_write_b32 v185, v213 offset:24144
	v_fmac_f32_e32 v27, v160, v26
	v_fmac_f32_e32 v207, v160, v206
	v_cvt_pk_bf16_f32 v214, v26, v206
	v_fma_f32 v27, -v161, v206, v27
	v_fmac_f32_e32 v207, v161, v26
	ds_write_b32 v185, v214 offset:24416
	v_fmac_f32_e32 v12, v160, v27
	v_fmac_f32_e32 v44, v160, v207
	v_cvt_pk_bf16_f32 v215, v27, v207
	v_fma_f32 v12, -v161, v207, v12
	v_fmac_f32_e32 v44, v161, v27
	ds_write_b32 v185, v215 offset:24688
	v_fmac_f32_e32 v13, v160, v12
	v_fmac_f32_e32 v45, v160, v44
	v_cvt_pk_bf16_f32 v212, v12, v44
	v_fma_f32 v13, -v161, v44, v13
	v_fmac_f32_e32 v45, v161, v12
	ds_write_b32 v185, v212 offset:24960
	v_fmac_f32_e32 v14, v160, v13
	v_fmac_f32_e32 v46, v160, v45
	v_cvt_pk_bf16_f32 v213, v13, v45
	v_fma_f32 v14, -v161, v45, v14
	v_fmac_f32_e32 v46, v161, v13
	ds_write_b32 v185, v213 offset:25232
	v_fmac_f32_e32 v15, v160, v14
	v_fmac_f32_e32 v47, v160, v46
	v_cvt_pk_bf16_f32 v214, v14, v46
	v_fma_f32 v15, -v161, v46, v15
	v_fmac_f32_e32 v47, v161, v14
	ds_write_b32 v185, v214 offset:25504
	v_fmac_f32_e32 v28, v160, v15
	v_fmac_f32_e32 v208, v160, v47
	v_cvt_pk_bf16_f32 v215, v15, v47
	v_fma_f32 v28, -v161, v47, v28
	v_fmac_f32_e32 v208, v161, v15
	ds_write_b32 v185, v215 offset:25776
	v_fmac_f32_e32 v29, v160, v28
	v_fmac_f32_e32 v209, v160, v208
	v_cvt_pk_bf16_f32 v212, v28, v208
	v_fma_f32 v29, -v161, v208, v29
	v_fmac_f32_e32 v209, v161, v28
	ds_write_b32 v185, v212 offset:26048
	v_fmac_f32_e32 v30, v160, v29
	v_fmac_f32_e32 v210, v160, v209
	v_cvt_pk_bf16_f32 v213, v29, v209
	v_fma_f32 v30, -v161, v209, v30
	v_fmac_f32_e32 v210, v161, v29
	ds_write_b32 v185, v213 offset:26320
	v_fmac_f32_e32 v31, v160, v30
	v_fmac_f32_e32 v211, v160, v210
	v_cvt_pk_bf16_f32 v214, v30, v210
	v_fma_f32 v31, -v161, v210, v31
	v_fmac_f32_e32 v211, v161, v30
	ds_write_b32 v185, v214 offset:26592
	v_mov_b32_e32 v188, v31
	v_mov_b32_e32 v189, v211
	v_cvt_pk_bf16_f32 v215, v31, v211
	ds_write_b32 v185, v215 offset:26864
	s_waitcnt lgkmcnt(0)
	ds_read_b128 v[32:35], v186 offset:18432
	ds_read_b128 v[36:39], v186 offset:18464
	ds_read_b128 v[40:43], v186 offset:18496
	ds_read_b128 v[44:47], v186 offset:18528
	ds_read_b128 v[196:199], v186 offset:18560
	ds_read_b128 v[200:203], v186 offset:18592
	ds_read_b128 v[204:207], v186 offset:18624
	ds_read_b128 v[208:211], v186 offset:18656
	s_waitcnt lgkmcnt(7)
	v_mfma_f32_32x32x16_bf16 v[234:249], v[64:67], v[32:35], 0
	v_fmac_f32_e32 v48, v100, v228
	v_fmac_f32_e32 v49, v101, v229
	v_fmac_f32_e32 v50, v102, v230
	v_fmac_f32_e32 v51, v103, v231
	v_fmac_f32_e32 v52, v80, v232
	v_fmac_f32_e32 v53, v81, v233
	v_fmac_f32_e32 v54, v82, v251
	v_fmac_f32_e32 v55, v83, v252
	v_mul_f32_e32 v56, v48, v48
	s_waitcnt lgkmcnt(6)
	v_mfma_f32_32x32x16_bf16 v[234:249], v[68:71], v[36:39], v[234:249]
	v_mul_f32_e32 v57, v49, v49
	v_mul_f32_e32 v58, v50, v50
	v_mul_f32_e32 v59, v51, v51
	v_mul_f32_e32 v60, v52, v52
	v_mul_f32_e32 v61, v53, v53
	v_mul_f32_e32 v62, v54, v54
	v_mul_f32_e32 v63, v55, v55
	v_fmaak_f32 v56, v56, v184, 0xc0135761
	v_fmaak_f32 v57, v57, v184, 0xc0135761
	s_waitcnt lgkmcnt(5)
	v_mfma_f32_32x32x16_bf16 v[234:249], v[72:75], v[40:43], v[234:249]
	v_fmaak_f32 v58, v58, v184, 0xc0135761
	v_fmaak_f32 v59, v59, v184, 0xc0135761
	v_fmaak_f32 v60, v60, v184, 0xc0135761
	v_fmaak_f32 v61, v61, v184, 0xc0135761
	v_fmaak_f32 v62, v62, v184, 0xc0135761
	v_fmaak_f32 v63, v63, v184, 0xc0135761
	v_mul_f32_e32 v56, v48, v56
	v_mul_f32_e32 v57, v49, v57
	v_mul_f32_e32 v58, v50, v58
	s_waitcnt lgkmcnt(4)
	v_mfma_f32_32x32x16_bf16 v[234:249], v[76:79], v[44:47], v[234:249]
	v_mul_f32_e32 v59, v51, v59
	v_mul_f32_e32 v60, v52, v60
	v_mul_f32_e32 v61, v53, v61
	v_mul_f32_e32 v62, v54, v62
	v_mul_f32_e32 v63, v55, v63
	v_exp_f32_e32 v56, v56
	v_exp_f32_e32 v57, v57
	v_exp_f32_e32 v58, v58
	v_exp_f32_e32 v59, v59
	s_waitcnt lgkmcnt(3)
	v_mfma_f32_32x32x16_bf16 v[234:249], v[84:87], v[196:199], v[234:249]
	v_exp_f32_e32 v60, v60
	v_exp_f32_e32 v61, v61
	v_exp_f32_e32 v62, v62
	v_exp_f32_e32 v63, v63
	v_add_f32_e32 v56, 1.0, v56
	v_add_f32_e32 v57, 1.0, v57
	v_add_f32_e32 v58, 1.0, v58
	v_add_f32_e32 v59, 1.0, v59
	s_waitcnt lgkmcnt(2)
	v_mfma_f32_32x32x16_bf16 v[234:249], v[88:91], v[200:203], v[234:249]
	v_add_f32_e32 v60, 1.0, v60
	v_add_f32_e32 v61, 1.0, v61
	v_add_f32_e32 v62, 1.0, v62
	v_add_f32_e32 v63, 1.0, v63
	v_rcp_f32_e32 v56, v56
	v_rcp_f32_e32 v57, v57
	v_rcp_f32_e32 v58, v58
	v_rcp_f32_e32 v59, v59
	s_waitcnt lgkmcnt(1)
	v_mfma_f32_32x32x16_bf16 v[234:249], v[96:99], v[204:207], v[234:249]
	v_rcp_f32_e32 v60, v60
	v_rcp_f32_e32 v61, v61
	v_rcp_f32_e32 v62, v62
	v_rcp_f32_e32 v63, v63
	v_mul_f32_e32 v48, v48, v56
	v_mul_f32_e32 v49, v49, v57
	v_mul_f32_e32 v50, v50, v58
	v_mul_f32_e32 v51, v51, v59
	s_waitcnt lgkmcnt(0)
	v_mfma_f32_32x32x16_bf16 v[234:249], v[108:111], v[208:211], v[234:249]
	v_mul_f32_e32 v52, v52, v60
	v_mul_f32_e32 v53, v53, v61
	v_mul_f32_e32 v54, v54, v62
	v_mul_f32_e32 v55, v55, v63
	v_cvt_pk_bf16_f32 v56, v48, v49
	v_cvt_pk_bf16_f32 v57, v50, v51
	v_cvt_pk_bf16_f32 v58, v52, v53
	v_cvt_pk_bf16_f32 v59, v54, v55
	global_store_dwordx2 v253, v[56:57], s[14:15]
	global_store_dwordx2 v254, v[58:59], s[14:15]
	s_movk_i32 s18, 0x1000
	s_and_b32 s17, s16, 0x3800
	s_cmp_eq_u32 s17, 0x800
	s_cselect_b32 s18, 0x1f9000, s18
	s_add_u32 s14, s14, s18
	s_addc_u32 s15, s15, 0
	s_cmp_eq_u32 s0, 0x1080000
	s_cbranch_scc0 .Lscan_tile
	s_nop 11
	v_fmac_f32_e32 v234, v100, v162
	v_fmac_f32_e32 v235, v101, v163
	v_fmac_f32_e32 v236, v102, v164
	v_fmac_f32_e32 v237, v103, v165
	v_fmac_f32_e32 v238, v80, v166
	v_fmac_f32_e32 v239, v81, v167
	v_fmac_f32_e32 v240, v82, v192
	v_fmac_f32_e32 v241, v83, v193
	v_mul_f32_e32 v242, v234, v234
	v_mul_f32_e32 v243, v235, v235
	v_mul_f32_e32 v244, v236, v236
	v_mul_f32_e32 v245, v237, v237
	v_mul_f32_e32 v246, v238, v238
	v_mul_f32_e32 v247, v239, v239
	v_mul_f32_e32 v248, v240, v240
	v_mul_f32_e32 v249, v241, v241
	v_fmaak_f32 v242, v242, v184, 0xc0135761
	v_fmaak_f32 v243, v243, v184, 0xc0135761
	v_fmaak_f32 v244, v244, v184, 0xc0135761
	v_fmaak_f32 v245, v245, v184, 0xc0135761
	v_fmaak_f32 v246, v246, v184, 0xc0135761
	v_fmaak_f32 v247, v247, v184, 0xc0135761
	v_fmaak_f32 v248, v248, v184, 0xc0135761
	v_fmaak_f32 v249, v249, v184, 0xc0135761
	v_mul_f32_e32 v242, v234, v242
	v_mul_f32_e32 v243, v235, v243
	v_mul_f32_e32 v244, v236, v244
	v_mul_f32_e32 v245, v237, v245
	v_mul_f32_e32 v246, v238, v246
	v_mul_f32_e32 v247, v239, v247
	v_mul_f32_e32 v248, v240, v248
	v_mul_f32_e32 v249, v241, v249
	v_exp_f32_e32 v242, v242
	v_exp_f32_e32 v243, v243
	v_exp_f32_e32 v244, v244
	v_exp_f32_e32 v245, v245
	v_exp_f32_e32 v246, v246
	v_exp_f32_e32 v247, v247
	v_exp_f32_e32 v248, v248
	v_exp_f32_e32 v249, v249
	v_add_f32_e32 v242, 1.0, v242
	v_add_f32_e32 v243, 1.0, v243
	v_add_f32_e32 v244, 1.0, v244
	v_add_f32_e32 v245, 1.0, v245
	v_add_f32_e32 v246, 1.0, v246
	v_add_f32_e32 v247, 1.0, v247
	v_add_f32_e32 v248, 1.0, v248
	v_add_f32_e32 v249, 1.0, v249
	v_rcp_f32_e32 v242, v242
	v_rcp_f32_e32 v243, v243
	v_rcp_f32_e32 v244, v244
	v_rcp_f32_e32 v245, v245
	v_rcp_f32_e32 v246, v246
	v_rcp_f32_e32 v247, v247
	v_rcp_f32_e32 v248, v248
	v_rcp_f32_e32 v249, v249
	v_mul_f32_e32 v234, v234, v242
	v_mul_f32_e32 v235, v235, v243
	v_mul_f32_e32 v236, v236, v244
	v_mul_f32_e32 v237, v237, v245
	v_mul_f32_e32 v238, v238, v246
	v_mul_f32_e32 v239, v239, v247
	v_mul_f32_e32 v240, v240, v248
	v_mul_f32_e32 v241, v241, v249
	v_cvt_pk_bf16_f32 v242, v234, v235
	v_cvt_pk_bf16_f32 v243, v236, v237
	v_cvt_pk_bf16_f32 v244, v238, v239
	v_cvt_pk_bf16_f32 v245, v240, v241
	global_store_dwordx2 v253, v[242:243], s[14:15]
	global_store_dwordx2 v254, v[244:245], s[14:15]
	s_add_i32 s6, s6, s7
	s_add_i32 s10, s10, s11
	s_add_i32 s12, s12, s7
	s_cmpk_gt_i32 s6, 0x3ff
	s_cbranch_scc0 .LBB0_563
